# K-loop bottom barrier rotated to loop top in all 7 GEMM loops (trailing half runs last MFMA block straight into epilogue)
# baseline (speedup 1.0000x reference)
.LBB0_91:
	s_ashr_i32 s53, s52, 31
	s_lshl_b64 s[10:11], s[52:53], 19
	s_add_u32 s54, s68, s10
	s_addc_u32 s55, s69, s11
	s_and_b64 s[10:11], s[40:41], exec
	s_cselect_b32 s5, s55, s7
	s_cselect_b32 s24, s54, s6
	s_ashr_i32 s51, s50, 31
	s_lshl_b64 s[10:11], s[50:51], 19
	s_add_u32 s56, s15, s10
	s_addc_u32 s57, s26, s11
	s_and_b64 s[10:11], s[40:41], exec
	s_cselect_b32 s47, s57, s9
	s_cselect_b32 s51, s56, s8
	s_add_u32 s6, s6, 0x40080
	s_addc_u32 s7, s7, 0
	s_add_u32 s53, s8, 0x100
	v_mov_b32_e32 v0, 0
	v_mov_b32_e32 v251, 0x260
	v_mov_b32_e32 v224, 0x3e124925
	v_mov_b32_e32 v223, 0x3e2aaaab
	v_mov_b32_e32 v222, 0x3e4ccccd
	v_mov_b32_e32 v221, 0x3e800000
	v_mov_b32_e32 v220, 0x3eaaaaab
	s_addc_u32 s58, s9, 0
	s_mov_b32 s59, -2
	v_mov_b32_e32 v1, v0
	v_mov_b32_e32 v2, v0
	v_mov_b32_e32 v3, v0
	v_mov_b32_e32 v4, v0
	v_mov_b32_e32 v5, v0
	v_mov_b32_e32 v6, v0
	v_mov_b32_e32 v7, v0
	v_mov_b32_e32 v16, v0
	v_mov_b32_e32 v17, v0
	v_mov_b32_e32 v18, v0
	v_mov_b32_e32 v19, v0
	v_mov_b32_e32 v20, v0
	v_mov_b32_e32 v21, v0
	v_mov_b32_e32 v22, v0
	v_mov_b32_e32 v23, v0
	v_mov_b32_e32 v32, v0
	v_mov_b32_e32 v33, v0
	v_mov_b32_e32 v34, v0
	v_mov_b32_e32 v35, v0
	v_mov_b32_e32 v36, v0
	v_mov_b32_e32 v37, v0
	v_mov_b32_e32 v38, v0
	v_mov_b32_e32 v39, v0
	v_mov_b32_e32 v48, v0
	v_mov_b32_e32 v49, v0
	v_mov_b32_e32 v50, v0
	v_mov_b32_e32 v51, v0
	v_mov_b32_e32 v52, v0
	v_mov_b32_e32 v53, v0
	v_mov_b32_e32 v54, v0
	v_mov_b32_e32 v55, v0
	v_mov_b32_e32 v8, v0
	v_mov_b32_e32 v9, v0
	v_mov_b32_e32 v10, v0
	v_mov_b32_e32 v11, v0
	v_mov_b32_e32 v12, v0
	v_mov_b32_e32 v13, v0
	v_mov_b32_e32 v14, v0
	v_mov_b32_e32 v15, v0
	v_mov_b32_e32 v24, v0
	v_mov_b32_e32 v25, v0
	v_mov_b32_e32 v26, v0
	v_mov_b32_e32 v27, v0
	v_mov_b32_e32 v28, v0
	v_mov_b32_e32 v29, v0
	v_mov_b32_e32 v30, v0
	v_mov_b32_e32 v31, v0
	v_mov_b32_e32 v40, v0
	v_mov_b32_e32 v41, v0
	v_mov_b32_e32 v42, v0
	v_mov_b32_e32 v43, v0
	v_mov_b32_e32 v44, v0
	v_mov_b32_e32 v45, v0
	v_mov_b32_e32 v46, v0
	v_mov_b32_e32 v47, v0
	v_mov_b32_e32 v56, v0
	v_mov_b32_e32 v57, v0
	v_mov_b32_e32 v58, v0
	v_mov_b32_e32 v59, v0
	v_mov_b32_e32 v60, v0
	v_mov_b32_e32 v61, v0
	v_mov_b32_e32 v62, v0
	v_mov_b32_e32 v63, v0
	v_mov_b32_e32 v64, v0
	v_mov_b32_e32 v65, v0
	v_mov_b32_e32 v66, v0
	v_mov_b32_e32 v67, v0
	v_mov_b32_e32 v68, v0
	v_mov_b32_e32 v69, v0
	v_mov_b32_e32 v70, v0
	v_mov_b32_e32 v71, v0
	v_mov_b32_e32 v80, v0
	v_mov_b32_e32 v81, v0
	v_mov_b32_e32 v82, v0
	v_mov_b32_e32 v83, v0
	v_mov_b32_e32 v84, v0
	v_mov_b32_e32 v85, v0
	v_mov_b32_e32 v86, v0
	v_mov_b32_e32 v87, v0
	v_mov_b32_e32 v96, v0
	v_mov_b32_e32 v97, v0
	v_mov_b32_e32 v98, v0
	v_mov_b32_e32 v99, v0
	v_mov_b32_e32 v100, v0
	v_mov_b32_e32 v101, v0
	v_mov_b32_e32 v102, v0
	v_mov_b32_e32 v103, v0
	v_mov_b32_e32 v112, v0
	v_mov_b32_e32 v113, v0
	v_mov_b32_e32 v114, v0
	v_mov_b32_e32 v115, v0
	v_mov_b32_e32 v116, v0
	v_mov_b32_e32 v117, v0
	v_mov_b32_e32 v118, v0
	v_mov_b32_e32 v119, v0
	v_mov_b32_e32 v72, v0
	v_mov_b32_e32 v73, v0
	v_mov_b32_e32 v74, v0
	v_mov_b32_e32 v75, v0
	v_mov_b32_e32 v76, v0
	v_mov_b32_e32 v77, v0
	v_mov_b32_e32 v78, v0
	v_mov_b32_e32 v79, v0
	v_mov_b32_e32 v88, v0
	v_mov_b32_e32 v89, v0
	v_mov_b32_e32 v90, v0
	v_mov_b32_e32 v91, v0
	v_mov_b32_e32 v92, v0
	v_mov_b32_e32 v93, v0
	v_mov_b32_e32 v94, v0
	v_mov_b32_e32 v95, v0
	v_mov_b32_e32 v104, v0
	v_mov_b32_e32 v105, v0
	v_mov_b32_e32 v106, v0
	v_mov_b32_e32 v107, v0
	v_mov_b32_e32 v108, v0
	v_mov_b32_e32 v109, v0
	v_mov_b32_e32 v110, v0
	v_mov_b32_e32 v111, v0
	v_mov_b32_e32 v120, v0
	v_mov_b32_e32 v121, v0
	v_mov_b32_e32 v122, v0
	v_mov_b32_e32 v123, v0
	v_mov_b32_e32 v124, v0
	v_mov_b32_e32 v125, v0
	v_mov_b32_e32 v126, v0
	v_mov_b32_e32 v127, v0
	s_branch .Lrot_92
.LBB0_92:
	s_barrier
.Lrot_92:
	s_add_u32 s8, s6, 0xfffc0080
	s_addc_u32 s9, s7, -1
	s_add_i32 s35, 0, 0x10000
	s_cmp_eq_u32 s59, 12
	s_cselect_b32 s11, s5, s9
	s_cselect_b32 s10, s24, s8
	v_add_u32_e32 v140, s35, v165
	s_cselect_b32 s9, s47, s58
	s_cselect_b32 s8, s51, s53
	s_add_i32 s74, 0, 0x14000
	ds_read_b128 v[142:145], v140
	ds_read_b128 v[146:149], v140 offset:1024
	ds_read_b128 v[150:153], v140 offset:2048
	ds_read_b128 v[154:157], v140 offset:3072
	v_add_u32_e32 v140, s74, v165
	ds_read_b128 v[158:161], v140
	ds_read_b128 v[168:171], v140 offset:1024
	ds_read_b128 v[172:175], v140 offset:2048
	ds_read_b128 v[176:179], v140 offset:3072
	v_lshl_add_u64 v[162:163], s[6:7], 0, v[136:137]
	s_add_i32 m0, s27, 0xc000
	ds_read_b128 v[180:183], v166
	ds_read_b128 v[184:187], v166 offset:1024
	ds_read_b128 v[188:191], v166 offset:2048
	ds_read_b128 v[192:195], v166 offset:3072
	ds_read_b128 v[200:203], v166 offset:4096
	ds_read_b128 v[206:209], v166 offset:5120
	ds_read_b128 v[210:213], v166 offset:6144
	ds_read_b128 v[214:217], v166 offset:7168
	global_load_lds_dwordx4 v[162:163], off
	v_lshl_add_u64 v[162:163], s[6:7], 0, v[138:139]
	s_add_i32 m0, s27, 0xe000
	s_nop 0
	global_load_lds_dwordx4 v[162:163], off
	s_waitcnt vmcnt(8)
	s_waitcnt lgkmcnt(0)
	s_barrier
	s_setprio 1
	s_waitcnt lgkmcnt(0)
	v_mfma_f32_16x16x32_bf16 v[124:127], v[142:145], v[180:183], v[124:127]
	v_mfma_f32_16x16x32_bf16 v[120:123], v[150:153], v[180:183], v[120:123]
	v_mfma_f32_16x16x32_bf16 v[108:111], v[142:145], v[188:191], v[108:111]
	v_mfma_f32_16x16x32_bf16 v[104:107], v[150:153], v[188:191], v[104:107]
	v_mfma_f32_16x16x32_bf16 v[92:95], v[142:145], v[200:203], v[92:95]
	v_mfma_f32_16x16x32_bf16 v[88:91], v[150:153], v[200:203], v[88:91]
	v_mfma_f32_16x16x32_bf16 v[76:79], v[142:145], v[210:213], v[76:79]
	v_mfma_f32_16x16x32_bf16 v[72:75], v[150:153], v[210:213], v[72:75]
	v_mfma_f32_16x16x32_bf16 v[124:127], v[146:149], v[184:187], v[124:127]
	v_mfma_f32_16x16x32_bf16 v[120:123], v[154:157], v[184:187], v[120:123]
	v_mfma_f32_16x16x32_bf16 v[108:111], v[146:149], v[192:195], v[108:111]
	v_mfma_f32_16x16x32_bf16 v[104:107], v[154:157], v[192:195], v[104:107]
	v_mfma_f32_16x16x32_bf16 v[92:95], v[146:149], v[206:209], v[92:95]
	v_mfma_f32_16x16x32_bf16 v[88:91], v[154:157], v[206:209], v[88:91]
	v_mfma_f32_16x16x32_bf16 v[76:79], v[146:149], v[214:217], v[76:79]
	v_mfma_f32_16x16x32_bf16 v[72:75], v[154:157], v[214:217], v[72:75]
	s_setprio 0
	s_setprio 1
	v_mfma_f32_16x16x32_bf16 v[116:119], v[158:161], v[180:183], v[116:119]
	v_mfma_f32_16x16x32_bf16 v[112:115], v[172:175], v[180:183], v[112:115]
	v_mfma_f32_16x16x32_bf16 v[100:103], v[158:161], v[188:191], v[100:103]
	v_mfma_f32_16x16x32_bf16 v[96:99], v[172:175], v[188:191], v[96:99]
	v_mfma_f32_16x16x32_bf16 v[84:87], v[158:161], v[200:203], v[84:87]
	v_mfma_f32_16x16x32_bf16 v[80:83], v[172:175], v[200:203], v[80:83]
	v_mfma_f32_16x16x32_bf16 v[68:71], v[158:161], v[210:213], v[68:71]
	v_mfma_f32_16x16x32_bf16 v[64:67], v[172:175], v[210:213], v[64:67]
	v_mfma_f32_16x16x32_bf16 v[116:119], v[168:171], v[184:187], v[116:119]
	v_mfma_f32_16x16x32_bf16 v[112:115], v[176:179], v[184:187], v[112:115]
	v_mfma_f32_16x16x32_bf16 v[100:103], v[168:171], v[192:195], v[100:103]
	v_mfma_f32_16x16x32_bf16 v[96:99], v[176:179], v[192:195], v[96:99]
	v_mfma_f32_16x16x32_bf16 v[84:87], v[168:171], v[206:209], v[84:87]
	v_mfma_f32_16x16x32_bf16 v[80:83], v[176:179], v[206:209], v[80:83]
	v_mfma_f32_16x16x32_bf16 v[68:71], v[168:171], v[214:217], v[68:71]
	v_mfma_f32_16x16x32_bf16 v[64:67], v[176:179], v[214:217], v[64:67]
	s_setprio 0
	s_barrier
	s_add_i32 s35, s35, s13
	v_lshl_add_u64 v[162:163], s[8:9], 0, v[132:133]
	s_mov_b32 m0, s35
	ds_read_b128 v[180:183], v166 offset:16384
	ds_read_b128 v[184:187], v166 offset:17408
	ds_read_b128 v[188:191], v166 offset:18432
	ds_read_b128 v[192:195], v166 offset:19456
	ds_read_b128 v[200:203], v166 offset:20480
	ds_read_b128 v[206:209], v166 offset:21504
	ds_read_b128 v[210:213], v166 offset:22528
	ds_read_b128 v[214:217], v166 offset:23552
	global_load_lds_dwordx4 v[162:163], off
	s_add_i32 m0, s35, 0x2000
	s_add_u32 s60, s8, 0x40000
	v_lshl_add_u64 v[196:197], s[8:9], 0, v[128:129]
	s_addc_u32 s61, s9, 0
	s_add_i32 s35, s74, s13
	global_load_lds_dwordx4 v[196:197], off
	v_lshl_add_u64 v[198:199], s[60:61], 0, v[132:133]
	s_mov_b32 m0, s35
	v_lshl_add_u64 v[204:205], s[10:11], 0, v[130:131]
	global_load_lds_dwordx4 v[198:199], off
	v_lshl_add_u64 v[198:199], s[60:61], 0, v[128:129]
	s_add_i32 m0, s35, 0x2000
	s_nop 0
	global_load_lds_dwordx4 v[198:199], off
	v_lshl_add_u64 v[198:199], s[10:11], 0, v[134:135]
	s_mov_b32 m0, s27
	s_nop 0
	global_load_lds_dwordx4 v[198:199], off
	s_mov_b32 m0, s28
	s_nop 0
	global_load_lds_dwordx4 v[204:205], off
	s_waitcnt vmcnt(8)
	s_waitcnt lgkmcnt(0)
	s_barrier
	s_setprio 1
	s_waitcnt lgkmcnt(0)
	v_mfma_f32_16x16x32_bf16 v[60:63], v[142:145], v[180:183], v[60:63]
	v_mfma_f32_16x16x32_bf16 v[56:59], v[150:153], v[180:183], v[56:59]
	v_mfma_f32_16x16x32_bf16 v[44:47], v[142:145], v[188:191], v[44:47]
	v_mfma_f32_16x16x32_bf16 v[40:43], v[150:153], v[188:191], v[40:43]
	v_mfma_f32_16x16x32_bf16 v[28:31], v[142:145], v[200:203], v[28:31]
	v_mfma_f32_16x16x32_bf16 v[24:27], v[150:153], v[200:203], v[24:27]
	v_mfma_f32_16x16x32_bf16 v[12:15], v[142:145], v[210:213], v[12:15]
	v_mfma_f32_16x16x32_bf16 v[8:11], v[150:153], v[210:213], v[8:11]
	v_mfma_f32_16x16x32_bf16 v[60:63], v[146:149], v[184:187], v[60:63]
	v_mfma_f32_16x16x32_bf16 v[56:59], v[154:157], v[184:187], v[56:59]
	v_mfma_f32_16x16x32_bf16 v[44:47], v[146:149], v[192:195], v[44:47]
	v_mfma_f32_16x16x32_bf16 v[40:43], v[154:157], v[192:195], v[40:43]
	v_mfma_f32_16x16x32_bf16 v[28:31], v[146:149], v[206:209], v[28:31]
	v_mfma_f32_16x16x32_bf16 v[24:27], v[154:157], v[206:209], v[24:27]
	v_mfma_f32_16x16x32_bf16 v[12:15], v[146:149], v[214:217], v[12:15]
	v_mfma_f32_16x16x32_bf16 v[8:11], v[154:157], v[214:217], v[8:11]
	s_setprio 0
	s_setprio 1
	v_mfma_f32_16x16x32_bf16 v[52:55], v[158:161], v[180:183], v[52:55]
	v_mfma_f32_16x16x32_bf16 v[48:51], v[172:175], v[180:183], v[48:51]
	v_mfma_f32_16x16x32_bf16 v[36:39], v[158:161], v[188:191], v[36:39]
	v_mfma_f32_16x16x32_bf16 v[32:35], v[172:175], v[188:191], v[32:35]
	v_mfma_f32_16x16x32_bf16 v[20:23], v[158:161], v[200:203], v[20:23]
	v_mfma_f32_16x16x32_bf16 v[16:19], v[172:175], v[200:203], v[16:19]
	v_mfma_f32_16x16x32_bf16 v[4:7], v[158:161], v[210:213], v[4:7]
	v_mfma_f32_16x16x32_bf16 v[0:3], v[172:175], v[210:213], v[0:3]
	v_mfma_f32_16x16x32_bf16 v[52:55], v[168:171], v[184:187], v[52:55]
	v_mfma_f32_16x16x32_bf16 v[48:51], v[176:179], v[184:187], v[48:51]
	v_mfma_f32_16x16x32_bf16 v[36:39], v[168:171], v[192:195], v[36:39]
	v_mfma_f32_16x16x32_bf16 v[32:35], v[176:179], v[192:195], v[32:35]
	v_mfma_f32_16x16x32_bf16 v[20:23], v[168:171], v[206:209], v[20:23]
	v_mfma_f32_16x16x32_bf16 v[16:19], v[176:179], v[206:209], v[16:19]
	v_mfma_f32_16x16x32_bf16 v[4:7], v[168:171], v[214:217], v[4:7]
	v_mfma_f32_16x16x32_bf16 v[0:3], v[176:179], v[214:217], v[0:3]
	s_setprio 0
	s_barrier
	s_add_i32 s35, 0, 0x18000
	v_add_u32_e32 v140, s35, v165
	s_add_i32 s60, 0, 0x1c000
	ds_read_b128 v[142:145], v140
	ds_read_b128 v[146:149], v140 offset:1024
	ds_read_b128 v[150:153], v140 offset:2048
	ds_read_b128 v[154:157], v140 offset:3072
	v_add_u32_e32 v140, s60, v165
	ds_read_b128 v[158:161], v140
	ds_read_b128 v[168:171], v140 offset:1024
	ds_read_b128 v[172:175], v140 offset:2048
	ds_read_b128 v[176:179], v140 offset:3072
	s_add_u32 s10, s10, 0x40000
	s_addc_u32 s11, s11, 0
	s_mov_b32 m0, s29
	v_lshl_add_u64 v[218:219], s[10:11], 0, v[134:135]
	ds_read_b128 v[180:183], v166 offset:32768
	ds_read_b128 v[184:187], v166 offset:33792
	ds_read_b128 v[188:191], v166 offset:34816
	ds_read_b128 v[192:195], v166 offset:35840
	ds_read_b128 v[200:203], v166 offset:36864
	ds_read_b128 v[206:209], v166 offset:37888
	ds_read_b128 v[210:213], v166 offset:38912
	ds_read_b128 v[214:217], v166 offset:39936
	global_load_lds_dwordx4 v[218:219], off
	v_lshl_add_u64 v[218:219], s[10:11], 0, v[130:131]
	s_mov_b32 m0, s38
	s_nop 0
	global_load_lds_dwordx4 v[218:219], off
	s_waitcnt vmcnt(8)
	s_waitcnt lgkmcnt(0)
	s_barrier
	s_setprio 1
	s_waitcnt lgkmcnt(0)
	v_mfma_f32_16x16x32_bf16 v[124:127], v[142:145], v[180:183], v[124:127]
	v_mfma_f32_16x16x32_bf16 v[120:123], v[150:153], v[180:183], v[120:123]
	v_mfma_f32_16x16x32_bf16 v[108:111], v[142:145], v[188:191], v[108:111]
	v_mfma_f32_16x16x32_bf16 v[104:107], v[150:153], v[188:191], v[104:107]
	v_mfma_f32_16x16x32_bf16 v[92:95], v[142:145], v[200:203], v[92:95]
	v_mfma_f32_16x16x32_bf16 v[88:91], v[150:153], v[200:203], v[88:91]
	v_mfma_f32_16x16x32_bf16 v[76:79], v[142:145], v[210:213], v[76:79]
	v_mfma_f32_16x16x32_bf16 v[72:75], v[150:153], v[210:213], v[72:75]
	v_mfma_f32_16x16x32_bf16 v[124:127], v[146:149], v[184:187], v[124:127]
	v_mfma_f32_16x16x32_bf16 v[120:123], v[154:157], v[184:187], v[120:123]
	v_mfma_f32_16x16x32_bf16 v[108:111], v[146:149], v[192:195], v[108:111]
	v_mfma_f32_16x16x32_bf16 v[104:107], v[154:157], v[192:195], v[104:107]
	v_mfma_f32_16x16x32_bf16 v[92:95], v[146:149], v[206:209], v[92:95]
	v_mfma_f32_16x16x32_bf16 v[88:91], v[154:157], v[206:209], v[88:91]
	v_mfma_f32_16x16x32_bf16 v[76:79], v[146:149], v[214:217], v[76:79]
	v_mfma_f32_16x16x32_bf16 v[72:75], v[154:157], v[214:217], v[72:75]
	s_setprio 0
	s_setprio 1
	v_mfma_f32_16x16x32_bf16 v[116:119], v[158:161], v[180:183], v[116:119]
	v_mfma_f32_16x16x32_bf16 v[112:115], v[172:175], v[180:183], v[112:115]
	v_mfma_f32_16x16x32_bf16 v[100:103], v[158:161], v[188:191], v[100:103]
	v_mfma_f32_16x16x32_bf16 v[96:99], v[172:175], v[188:191], v[96:99]
	v_mfma_f32_16x16x32_bf16 v[84:87], v[158:161], v[200:203], v[84:87]
	v_mfma_f32_16x16x32_bf16 v[80:83], v[172:175], v[200:203], v[80:83]
	v_mfma_f32_16x16x32_bf16 v[68:71], v[158:161], v[210:213], v[68:71]
	v_mfma_f32_16x16x32_bf16 v[64:67], v[172:175], v[210:213], v[64:67]
	v_mfma_f32_16x16x32_bf16 v[116:119], v[168:171], v[184:187], v[116:119]
	v_mfma_f32_16x16x32_bf16 v[112:115], v[176:179], v[184:187], v[112:115]
	v_mfma_f32_16x16x32_bf16 v[100:103], v[168:171], v[192:195], v[100:103]
	v_mfma_f32_16x16x32_bf16 v[96:99], v[176:179], v[192:195], v[96:99]
	v_mfma_f32_16x16x32_bf16 v[84:87], v[168:171], v[206:209], v[84:87]
	v_mfma_f32_16x16x32_bf16 v[80:83], v[176:179], v[206:209], v[80:83]
	v_mfma_f32_16x16x32_bf16 v[68:71], v[168:171], v[214:217], v[68:71]
	v_mfma_f32_16x16x32_bf16 v[64:67], v[176:179], v[214:217], v[64:67]
	s_setprio 0
	s_barrier
	s_add_i32 s10, s35, s13
	v_lshl_add_u64 v[162:163], v[162:163], 0, s[36:37]
	s_mov_b32 m0, s10
	ds_read_b128 v[180:183], v166 offset:49152
	ds_read_b128 v[184:187], v166 offset:50176
	ds_read_b128 v[188:191], v166 offset:51200
	ds_read_b128 v[192:195], v166 offset:52224
	ds_read_b128 v[200:203], v166 offset:53248
	ds_read_b128 v[206:209], v166 offset:54272
	ds_read_b128 v[210:213], v166 offset:55296
	ds_read_b128 v[214:217], v166 offset:56320
	global_load_lds_dwordx4 v[162:163], off
	s_add_i32 m0, s10, 0x2000
	s_add_u32 s8, s8, 0x40080
	v_lshl_add_u64 v[162:163], v[196:197], 0, s[36:37]
	s_addc_u32 s9, s9, 0
	s_add_i32 s10, s60, s13
	global_load_lds_dwordx4 v[162:163], off
	v_lshl_add_u64 v[162:163], s[8:9], 0, v[132:133]
	s_mov_b32 m0, s10
	s_nop 0
	global_load_lds_dwordx4 v[162:163], off
	v_lshl_add_u64 v[162:163], s[8:9], 0, v[128:129]
	s_add_i32 m0, s10, 0x2000
	s_nop 0
	global_load_lds_dwordx4 v[162:163], off
	v_lshl_add_u64 v[162:163], v[198:199], 0, s[36:37]
	s_mov_b32 m0, s42
	s_nop 0
	global_load_lds_dwordx4 v[162:163], off
	v_lshl_add_u64 v[162:163], v[204:205], 0, s[36:37]
	s_mov_b32 m0, s43
	s_nop 0
	global_load_lds_dwordx4 v[162:163], off
	s_waitcnt vmcnt(8)
	s_waitcnt lgkmcnt(0)
	s_barrier
	s_setprio 1
	s_waitcnt lgkmcnt(0)
	v_mfma_f32_16x16x32_bf16 v[60:63], v[142:145], v[180:183], v[60:63]
	v_mfma_f32_16x16x32_bf16 v[56:59], v[150:153], v[180:183], v[56:59]
	v_mfma_f32_16x16x32_bf16 v[44:47], v[142:145], v[188:191], v[44:47]
	v_mfma_f32_16x16x32_bf16 v[40:43], v[150:153], v[188:191], v[40:43]
	v_mfma_f32_16x16x32_bf16 v[28:31], v[142:145], v[200:203], v[28:31]
	v_mfma_f32_16x16x32_bf16 v[24:27], v[150:153], v[200:203], v[24:27]
	v_mfma_f32_16x16x32_bf16 v[12:15], v[142:145], v[210:213], v[12:15]
	v_mfma_f32_16x16x32_bf16 v[8:11], v[150:153], v[210:213], v[8:11]
	v_mfma_f32_16x16x32_bf16 v[60:63], v[146:149], v[184:187], v[60:63]
	v_mfma_f32_16x16x32_bf16 v[56:59], v[154:157], v[184:187], v[56:59]
	v_mfma_f32_16x16x32_bf16 v[44:47], v[146:149], v[192:195], v[44:47]
	v_mfma_f32_16x16x32_bf16 v[40:43], v[154:157], v[192:195], v[40:43]
	v_mfma_f32_16x16x32_bf16 v[28:31], v[146:149], v[206:209], v[28:31]
	v_mfma_f32_16x16x32_bf16 v[24:27], v[154:157], v[206:209], v[24:27]
	v_mfma_f32_16x16x32_bf16 v[12:15], v[146:149], v[214:217], v[12:15]
	v_mfma_f32_16x16x32_bf16 v[8:11], v[154:157], v[214:217], v[8:11]
	s_setprio 0
	s_setprio 1
	v_mfma_f32_16x16x32_bf16 v[52:55], v[158:161], v[180:183], v[52:55]
	v_mfma_f32_16x16x32_bf16 v[48:51], v[172:175], v[180:183], v[48:51]
	v_mfma_f32_16x16x32_bf16 v[36:39], v[158:161], v[188:191], v[36:39]
	v_mfma_f32_16x16x32_bf16 v[32:35], v[172:175], v[188:191], v[32:35]
	v_mfma_f32_16x16x32_bf16 v[20:23], v[158:161], v[200:203], v[20:23]
	v_mfma_f32_16x16x32_bf16 v[16:19], v[172:175], v[200:203], v[16:19]
	v_mfma_f32_16x16x32_bf16 v[4:7], v[158:161], v[210:213], v[4:7]
	v_mfma_f32_16x16x32_bf16 v[0:3], v[172:175], v[210:213], v[0:3]
	v_mfma_f32_16x16x32_bf16 v[52:55], v[168:171], v[184:187], v[52:55]
	v_mfma_f32_16x16x32_bf16 v[48:51], v[176:179], v[184:187], v[48:51]
	v_mfma_f32_16x16x32_bf16 v[36:39], v[168:171], v[192:195], v[36:39]
	v_mfma_f32_16x16x32_bf16 v[32:35], v[176:179], v[192:195], v[32:35]
	v_mfma_f32_16x16x32_bf16 v[20:23], v[168:171], v[206:209], v[20:23]
	v_mfma_f32_16x16x32_bf16 v[16:19], v[176:179], v[206:209], v[16:19]
	v_mfma_f32_16x16x32_bf16 v[4:7], v[168:171], v[214:217], v[4:7]
	v_mfma_f32_16x16x32_bf16 v[0:3], v[176:179], v[214:217], v[0:3]
	s_setprio 0
	s_add_i32 s59, s59, 2
	s_add_u32 s6, s6, 0x100
	s_addc_u32 s7, s7, 0
	s_add_u32 s53, s53, 0x100
	s_addc_u32 s58, s58, 0
	s_cmp_gt_u32 s59, 13
	s_cbranch_scc0 .LBB0_92
	s_and_b64 vcc, exec, s[48:49]
	s_cbranch_vccz .LBB0_95
	s_barrier

.LBB0_146:
	s_ashr_i32 s55, s54, 31
	s_lshl_b64 s[10:11], s[54:55], 19
	s_add_u32 s56, s86, s10
	s_addc_u32 s57, s87, s11
	s_and_b64 s[10:11], s[40:41], exec
	s_cselect_b32 s24, s57, s7
	s_cselect_b32 s38, s56, s6
	s_ashr_i32 s58, s54, 4
	s_ashr_i32 s53, s52, 31
	s_ashr_i32 s59, s58, 31
	s_lshl_b64 s[10:11], s[52:53], 19
	s_lshl_b64 s[58:59], s[58:59], 21
	s_add_u32 s10, s16, s10
	s_addc_u32 s11, s17, s11
	s_add_u32 s58, s10, s58
	s_addc_u32 s59, s11, s59
	s_and_b64 s[10:11], s[40:41], exec
	s_cselect_b32 s53, s59, s9
	s_cselect_b32 s55, s58, s8
	s_add_u32 s6, s6, 0x40080
	s_addc_u32 s7, s7, 0
	s_add_u32 s60, s8, 0x100
	v_mov_b32_e32 v0, 0
	v_mov_b32_e32 v251, 0x260
	v_mov_b32_e32 v220, 0x3e124925
	v_mov_b32_e32 v219, 0x3e2aaaab
	v_mov_b32_e32 v218, 0x3e4ccccd
	v_mov_b32_e32 v217, 0x3e800000
	v_mov_b32_e32 v216, 0x3eaaaaab
	s_addc_u32 s61, s9, 0
	s_mov_b32 s74, -2
	v_mov_b32_e32 v1, v0
	v_mov_b32_e32 v2, v0
	v_mov_b32_e32 v3, v0
	v_mov_b32_e32 v4, v0
	v_mov_b32_e32 v5, v0
	v_mov_b32_e32 v6, v0
	v_mov_b32_e32 v7, v0
	v_mov_b32_e32 v16, v0
	v_mov_b32_e32 v17, v0
	v_mov_b32_e32 v18, v0
	v_mov_b32_e32 v19, v0
	v_mov_b32_e32 v20, v0
	v_mov_b32_e32 v21, v0
	v_mov_b32_e32 v22, v0
	v_mov_b32_e32 v23, v0
	v_mov_b32_e32 v32, v0
	v_mov_b32_e32 v33, v0
	v_mov_b32_e32 v34, v0
	v_mov_b32_e32 v35, v0
	v_mov_b32_e32 v36, v0
	v_mov_b32_e32 v37, v0
	v_mov_b32_e32 v38, v0
	v_mov_b32_e32 v39, v0
	v_mov_b32_e32 v48, v0
	v_mov_b32_e32 v49, v0
	v_mov_b32_e32 v50, v0
	v_mov_b32_e32 v51, v0
	v_mov_b32_e32 v52, v0
	v_mov_b32_e32 v53, v0
	v_mov_b32_e32 v54, v0
	v_mov_b32_e32 v55, v0
	v_mov_b32_e32 v8, v0
	v_mov_b32_e32 v9, v0
	v_mov_b32_e32 v10, v0
	v_mov_b32_e32 v11, v0
	v_mov_b32_e32 v12, v0
	v_mov_b32_e32 v13, v0
	v_mov_b32_e32 v14, v0
	v_mov_b32_e32 v15, v0
	v_mov_b32_e32 v24, v0
	v_mov_b32_e32 v25, v0
	v_mov_b32_e32 v26, v0
	v_mov_b32_e32 v27, v0
	v_mov_b32_e32 v28, v0
	v_mov_b32_e32 v29, v0
	v_mov_b32_e32 v30, v0
	v_mov_b32_e32 v31, v0
	v_mov_b32_e32 v40, v0
	v_mov_b32_e32 v41, v0
	v_mov_b32_e32 v42, v0
	v_mov_b32_e32 v43, v0
	v_mov_b32_e32 v44, v0
	v_mov_b32_e32 v45, v0
	v_mov_b32_e32 v46, v0
	v_mov_b32_e32 v47, v0
	v_mov_b32_e32 v56, v0
	v_mov_b32_e32 v57, v0
	v_mov_b32_e32 v58, v0
	v_mov_b32_e32 v59, v0
	v_mov_b32_e32 v60, v0
	v_mov_b32_e32 v61, v0
	v_mov_b32_e32 v62, v0
	v_mov_b32_e32 v63, v0
	v_mov_b32_e32 v64, v0
	v_mov_b32_e32 v65, v0
	v_mov_b32_e32 v66, v0
	v_mov_b32_e32 v67, v0
	v_mov_b32_e32 v68, v0
	v_mov_b32_e32 v69, v0
	v_mov_b32_e32 v70, v0
	v_mov_b32_e32 v71, v0
	v_mov_b32_e32 v80, v0
	v_mov_b32_e32 v81, v0
	v_mov_b32_e32 v82, v0
	v_mov_b32_e32 v83, v0
	v_mov_b32_e32 v84, v0
	v_mov_b32_e32 v85, v0
	v_mov_b32_e32 v86, v0
	v_mov_b32_e32 v87, v0
	v_mov_b32_e32 v96, v0
	v_mov_b32_e32 v97, v0
	v_mov_b32_e32 v98, v0
	v_mov_b32_e32 v99, v0
	v_mov_b32_e32 v100, v0
	v_mov_b32_e32 v101, v0
	v_mov_b32_e32 v102, v0
	v_mov_b32_e32 v103, v0
	v_mov_b32_e32 v112, v0
	v_mov_b32_e32 v113, v0
	v_mov_b32_e32 v114, v0
	v_mov_b32_e32 v115, v0
	v_mov_b32_e32 v116, v0
	v_mov_b32_e32 v117, v0
	v_mov_b32_e32 v118, v0
	v_mov_b32_e32 v119, v0
	v_mov_b32_e32 v72, v0
	v_mov_b32_e32 v73, v0
	v_mov_b32_e32 v74, v0
	v_mov_b32_e32 v75, v0
	v_mov_b32_e32 v76, v0
	v_mov_b32_e32 v77, v0
	v_mov_b32_e32 v78, v0
	v_mov_b32_e32 v79, v0
	v_mov_b32_e32 v88, v0
	v_mov_b32_e32 v89, v0
	v_mov_b32_e32 v90, v0
	v_mov_b32_e32 v91, v0
	v_mov_b32_e32 v92, v0
	v_mov_b32_e32 v93, v0
	v_mov_b32_e32 v94, v0
	v_mov_b32_e32 v95, v0
	v_mov_b32_e32 v104, v0
	v_mov_b32_e32 v105, v0
	v_mov_b32_e32 v106, v0
	v_mov_b32_e32 v107, v0
	v_mov_b32_e32 v108, v0
	v_mov_b32_e32 v109, v0
	v_mov_b32_e32 v110, v0
	v_mov_b32_e32 v111, v0
	v_mov_b32_e32 v120, v0
	v_mov_b32_e32 v121, v0
	v_mov_b32_e32 v122, v0
	v_mov_b32_e32 v123, v0
	v_mov_b32_e32 v124, v0
	v_mov_b32_e32 v125, v0
	v_mov_b32_e32 v126, v0
	v_mov_b32_e32 v127, v0
	s_branch .Lrot_147

.Lrot_147:
	s_add_u32 s8, s6, 0xfffc0080
	s_addc_u32 s9, s7, -1
	s_add_i32 s35, 0, 0x10000
	s_cmp_eq_u32 s74, 12
	s_cselect_b32 s11, s24, s9
	s_cselect_b32 s10, s38, s8
	s_cselect_b32 s9, s53, s61
	s_cselect_b32 s8, s55, s60
	s_add_i32 s75, 0, 0x14000
	v_add_u32_e32 v142, s35, v178
	v_add_u32_e32 v168, s75, v178
	ds_read_b128 v[128:131], v142
	ds_read_b128 v[132:135], v142 offset:1024
	ds_read_b128 v[136:139], v142 offset:2048
	ds_read_b128 v[142:145], v142 offset:3072
	ds_read_b128 v[146:149], v168
	ds_read_b128 v[150:153], v168 offset:1024
	ds_read_b128 v[154:157], v168 offset:2048
	ds_read_b128 v[168:171], v168 offset:3072
	v_lshl_add_u64 v[176:177], s[6:7], 0, v[164:165]
	s_add_i32 m0, s15, 0xc000
	ds_read_b128 v[172:175], v179
	ds_read_b128 v[180:183], v179 offset:1024
	ds_read_b128 v[184:187], v179 offset:2048
	ds_read_b128 v[188:191], v179 offset:3072
	ds_read_b128 v[192:195], v179 offset:4096
	ds_read_b128 v[200:203], v179 offset:5120
	ds_read_b128 v[206:209], v179 offset:6144
	ds_read_b128 v[210:213], v179 offset:7168
	global_load_lds_dwordx4 v[176:177], off
	v_lshl_add_u64 v[176:177], s[6:7], 0, v[166:167]
	s_add_i32 m0, s15, 0xe000
	s_nop 0
	global_load_lds_dwordx4 v[176:177], off
	s_waitcnt vmcnt(8)
	s_waitcnt lgkmcnt(0)
	s_barrier
	s_setprio 1
	s_waitcnt lgkmcnt(0)
	v_mfma_f32_16x16x32_bf16 v[124:127], v[128:131], v[172:175], v[124:127]
	v_mfma_f32_16x16x32_bf16 v[120:123], v[136:139], v[172:175], v[120:123]
	v_mfma_f32_16x16x32_bf16 v[108:111], v[128:131], v[184:187], v[108:111]
	v_mfma_f32_16x16x32_bf16 v[104:107], v[136:139], v[184:187], v[104:107]
	v_mfma_f32_16x16x32_bf16 v[92:95], v[128:131], v[192:195], v[92:95]
	v_mfma_f32_16x16x32_bf16 v[88:91], v[136:139], v[192:195], v[88:91]
	v_mfma_f32_16x16x32_bf16 v[76:79], v[128:131], v[206:209], v[76:79]
	v_mfma_f32_16x16x32_bf16 v[72:75], v[136:139], v[206:209], v[72:75]
	v_mfma_f32_16x16x32_bf16 v[124:127], v[132:135], v[180:183], v[124:127]
	v_mfma_f32_16x16x32_bf16 v[120:123], v[142:145], v[180:183], v[120:123]
	v_mfma_f32_16x16x32_bf16 v[108:111], v[132:135], v[188:191], v[108:111]
	v_mfma_f32_16x16x32_bf16 v[104:107], v[142:145], v[188:191], v[104:107]
	v_mfma_f32_16x16x32_bf16 v[92:95], v[132:135], v[200:203], v[92:95]
	v_mfma_f32_16x16x32_bf16 v[88:91], v[142:145], v[200:203], v[88:91]
	v_mfma_f32_16x16x32_bf16 v[76:79], v[132:135], v[210:213], v[76:79]
	v_mfma_f32_16x16x32_bf16 v[72:75], v[142:145], v[210:213], v[72:75]
	s_setprio 0
	s_setprio 1
	v_mfma_f32_16x16x32_bf16 v[116:119], v[146:149], v[172:175], v[116:119]
	v_mfma_f32_16x16x32_bf16 v[112:115], v[154:157], v[172:175], v[112:115]
	v_mfma_f32_16x16x32_bf16 v[100:103], v[146:149], v[184:187], v[100:103]
	v_mfma_f32_16x16x32_bf16 v[96:99], v[154:157], v[184:187], v[96:99]
	v_mfma_f32_16x16x32_bf16 v[84:87], v[146:149], v[192:195], v[84:87]
	v_mfma_f32_16x16x32_bf16 v[80:83], v[154:157], v[192:195], v[80:83]
	v_mfma_f32_16x16x32_bf16 v[68:71], v[146:149], v[206:209], v[68:71]
	v_mfma_f32_16x16x32_bf16 v[64:67], v[154:157], v[206:209], v[64:67]
	v_mfma_f32_16x16x32_bf16 v[116:119], v[150:153], v[180:183], v[116:119]
	v_mfma_f32_16x16x32_bf16 v[112:115], v[168:171], v[180:183], v[112:115]
	v_mfma_f32_16x16x32_bf16 v[100:103], v[150:153], v[188:191], v[100:103]
	v_mfma_f32_16x16x32_bf16 v[96:99], v[168:171], v[188:191], v[96:99]
	v_mfma_f32_16x16x32_bf16 v[84:87], v[150:153], v[200:203], v[84:87]
	v_mfma_f32_16x16x32_bf16 v[80:83], v[168:171], v[200:203], v[80:83]
	v_mfma_f32_16x16x32_bf16 v[68:71], v[150:153], v[210:213], v[68:71]
	v_mfma_f32_16x16x32_bf16 v[64:67], v[168:171], v[210:213], v[64:67]
	s_setprio 0
	s_barrier
	s_add_i32 s35, s35, s13
	v_lshl_add_u64 v[176:177], s[8:9], 0, v[140:141]
	s_mov_b32 m0, s35
	ds_read_b128 v[172:175], v179 offset:16384
	ds_read_b128 v[180:183], v179 offset:17408
	ds_read_b128 v[184:187], v179 offset:18432
	ds_read_b128 v[188:191], v179 offset:19456
	ds_read_b128 v[192:195], v179 offset:20480
	ds_read_b128 v[200:203], v179 offset:21504
	ds_read_b128 v[206:209], v179 offset:22528
	ds_read_b128 v[210:213], v179 offset:23552
	global_load_lds_dwordx4 v[176:177], off
	s_add_i32 m0, s35, 0x2000
	s_add_u32 s84, s8, 0x40000
	v_lshl_add_u64 v[196:197], s[8:9], 0, v[158:159]
	s_addc_u32 s85, s9, 0
	s_add_i32 s35, s75, s13
	global_load_lds_dwordx4 v[196:197], off
	v_lshl_add_u64 v[198:199], s[84:85], 0, v[140:141]
	s_mov_b32 m0, s35
	v_lshl_add_u64 v[204:205], s[10:11], 0, v[160:161]
	global_load_lds_dwordx4 v[198:199], off
	v_lshl_add_u64 v[198:199], s[84:85], 0, v[158:159]
	s_add_i32 m0, s35, 0x2000
	s_nop 0
	global_load_lds_dwordx4 v[198:199], off
	v_lshl_add_u64 v[198:199], s[10:11], 0, v[162:163]
	s_mov_b32 m0, s15
	s_nop 0
	global_load_lds_dwordx4 v[198:199], off
	s_mov_b32 m0, s26
	s_nop 0
	global_load_lds_dwordx4 v[204:205], off
	s_waitcnt vmcnt(8)
	s_waitcnt lgkmcnt(0)
	s_barrier
	s_setprio 1
	s_waitcnt lgkmcnt(0)
	v_mfma_f32_16x16x32_bf16 v[60:63], v[128:131], v[172:175], v[60:63]
	v_mfma_f32_16x16x32_bf16 v[56:59], v[136:139], v[172:175], v[56:59]
	v_mfma_f32_16x16x32_bf16 v[44:47], v[128:131], v[184:187], v[44:47]
	v_mfma_f32_16x16x32_bf16 v[40:43], v[136:139], v[184:187], v[40:43]
	v_mfma_f32_16x16x32_bf16 v[28:31], v[128:131], v[192:195], v[28:31]
	v_mfma_f32_16x16x32_bf16 v[24:27], v[136:139], v[192:195], v[24:27]
	v_mfma_f32_16x16x32_bf16 v[12:15], v[128:131], v[206:209], v[12:15]
	v_mfma_f32_16x16x32_bf16 v[8:11], v[136:139], v[206:209], v[8:11]
	v_mfma_f32_16x16x32_bf16 v[60:63], v[132:135], v[180:183], v[60:63]
	v_mfma_f32_16x16x32_bf16 v[56:59], v[142:145], v[180:183], v[56:59]
	v_mfma_f32_16x16x32_bf16 v[44:47], v[132:135], v[188:191], v[44:47]
	v_mfma_f32_16x16x32_bf16 v[40:43], v[142:145], v[188:191], v[40:43]
	v_mfma_f32_16x16x32_bf16 v[28:31], v[132:135], v[200:203], v[28:31]
	v_mfma_f32_16x16x32_bf16 v[24:27], v[142:145], v[200:203], v[24:27]
	v_mfma_f32_16x16x32_bf16 v[12:15], v[132:135], v[210:213], v[12:15]
	v_mfma_f32_16x16x32_bf16 v[8:11], v[142:145], v[210:213], v[8:11]
	s_setprio 0
	s_setprio 1
	v_mfma_f32_16x16x32_bf16 v[52:55], v[146:149], v[172:175], v[52:55]
	v_mfma_f32_16x16x32_bf16 v[48:51], v[154:157], v[172:175], v[48:51]
	v_mfma_f32_16x16x32_bf16 v[36:39], v[146:149], v[184:187], v[36:39]
	v_mfma_f32_16x16x32_bf16 v[32:35], v[154:157], v[184:187], v[32:35]
	v_mfma_f32_16x16x32_bf16 v[20:23], v[146:149], v[192:195], v[20:23]
	v_mfma_f32_16x16x32_bf16 v[16:19], v[154:157], v[192:195], v[16:19]
	v_mfma_f32_16x16x32_bf16 v[4:7], v[146:149], v[206:209], v[4:7]
	v_mfma_f32_16x16x32_bf16 v[0:3], v[154:157], v[206:209], v[0:3]
	v_mfma_f32_16x16x32_bf16 v[52:55], v[150:153], v[180:183], v[52:55]
	v_mfma_f32_16x16x32_bf16 v[48:51], v[168:171], v[180:183], v[48:51]
	v_mfma_f32_16x16x32_bf16 v[36:39], v[150:153], v[188:191], v[36:39]
	v_mfma_f32_16x16x32_bf16 v[32:35], v[168:171], v[188:191], v[32:35]
	v_mfma_f32_16x16x32_bf16 v[20:23], v[150:153], v[200:203], v[20:23]
	v_mfma_f32_16x16x32_bf16 v[16:19], v[168:171], v[200:203], v[16:19]
	v_mfma_f32_16x16x32_bf16 v[4:7], v[150:153], v[210:213], v[4:7]
	v_mfma_f32_16x16x32_bf16 v[0:3], v[168:171], v[210:213], v[0:3]
	s_setprio 0
	s_barrier
	s_add_i32 s35, 0, 0x18000
	s_add_i32 s75, 0, 0x1c000
	v_add_u32_e32 v142, s35, v178
	v_add_u32_e32 v168, s75, v178
	ds_read_b128 v[128:131], v142
	ds_read_b128 v[132:135], v142 offset:1024
	ds_read_b128 v[136:139], v142 offset:2048
	ds_read_b128 v[142:145], v142 offset:3072
	ds_read_b128 v[146:149], v168
	ds_read_b128 v[150:153], v168 offset:1024
	ds_read_b128 v[154:157], v168 offset:2048
	ds_read_b128 v[168:171], v168 offset:3072
	s_add_u32 s10, s10, 0x40000
	s_addc_u32 s11, s11, 0
	s_mov_b32 m0, s27
	v_lshl_add_u64 v[214:215], s[10:11], 0, v[162:163]
	ds_read_b128 v[172:175], v179 offset:32768
	ds_read_b128 v[180:183], v179 offset:33792
	ds_read_b128 v[184:187], v179 offset:34816
	ds_read_b128 v[188:191], v179 offset:35840
	ds_read_b128 v[192:195], v179 offset:36864
	ds_read_b128 v[200:203], v179 offset:37888
	ds_read_b128 v[206:209], v179 offset:38912
	ds_read_b128 v[210:213], v179 offset:39936
	global_load_lds_dwordx4 v[214:215], off
	v_lshl_add_u64 v[214:215], s[10:11], 0, v[160:161]
	s_mov_b32 m0, s28
	s_nop 0
	global_load_lds_dwordx4 v[214:215], off
	s_waitcnt vmcnt(8)
	s_waitcnt lgkmcnt(0)
	s_barrier
	s_setprio 1
	s_waitcnt lgkmcnt(0)
	v_mfma_f32_16x16x32_bf16 v[124:127], v[128:131], v[172:175], v[124:127]
	v_mfma_f32_16x16x32_bf16 v[120:123], v[136:139], v[172:175], v[120:123]
	v_mfma_f32_16x16x32_bf16 v[108:111], v[128:131], v[184:187], v[108:111]
	v_mfma_f32_16x16x32_bf16 v[104:107], v[136:139], v[184:187], v[104:107]
	v_mfma_f32_16x16x32_bf16 v[92:95], v[128:131], v[192:195], v[92:95]
	v_mfma_f32_16x16x32_bf16 v[88:91], v[136:139], v[192:195], v[88:91]
	v_mfma_f32_16x16x32_bf16 v[76:79], v[128:131], v[206:209], v[76:79]
	v_mfma_f32_16x16x32_bf16 v[72:75], v[136:139], v[206:209], v[72:75]
	v_mfma_f32_16x16x32_bf16 v[124:127], v[132:135], v[180:183], v[124:127]
	v_mfma_f32_16x16x32_bf16 v[120:123], v[142:145], v[180:183], v[120:123]
	v_mfma_f32_16x16x32_bf16 v[108:111], v[132:135], v[188:191], v[108:111]
	v_mfma_f32_16x16x32_bf16 v[104:107], v[142:145], v[188:191], v[104:107]
	v_mfma_f32_16x16x32_bf16 v[92:95], v[132:135], v[200:203], v[92:95]
	v_mfma_f32_16x16x32_bf16 v[88:91], v[142:145], v[200:203], v[88:91]
	v_mfma_f32_16x16x32_bf16 v[76:79], v[132:135], v[210:213], v[76:79]
	v_mfma_f32_16x16x32_bf16 v[72:75], v[142:145], v[210:213], v[72:75]
	s_setprio 0
	s_setprio 1
	v_mfma_f32_16x16x32_bf16 v[116:119], v[146:149], v[172:175], v[116:119]
	v_mfma_f32_16x16x32_bf16 v[112:115], v[154:157], v[172:175], v[112:115]
	v_mfma_f32_16x16x32_bf16 v[100:103], v[146:149], v[184:187], v[100:103]
	v_mfma_f32_16x16x32_bf16 v[96:99], v[154:157], v[184:187], v[96:99]
	v_mfma_f32_16x16x32_bf16 v[84:87], v[146:149], v[192:195], v[84:87]
	v_mfma_f32_16x16x32_bf16 v[80:83], v[154:157], v[192:195], v[80:83]
	v_mfma_f32_16x16x32_bf16 v[68:71], v[146:149], v[206:209], v[68:71]
	v_mfma_f32_16x16x32_bf16 v[64:67], v[154:157], v[206:209], v[64:67]
	v_mfma_f32_16x16x32_bf16 v[116:119], v[150:153], v[180:183], v[116:119]
	v_mfma_f32_16x16x32_bf16 v[112:115], v[168:171], v[180:183], v[112:115]
	v_mfma_f32_16x16x32_bf16 v[100:103], v[150:153], v[188:191], v[100:103]
	v_mfma_f32_16x16x32_bf16 v[96:99], v[168:171], v[188:191], v[96:99]
	v_mfma_f32_16x16x32_bf16 v[84:87], v[150:153], v[200:203], v[84:87]
	v_mfma_f32_16x16x32_bf16 v[80:83], v[168:171], v[200:203], v[80:83]
	v_mfma_f32_16x16x32_bf16 v[68:71], v[150:153], v[210:213], v[68:71]
	v_mfma_f32_16x16x32_bf16 v[64:67], v[168:171], v[210:213], v[64:67]
	s_setprio 0
	s_barrier
	s_add_i32 s10, s35, s13
	v_lshl_add_u64 v[176:177], v[176:177], 0, s[36:37]
	s_mov_b32 m0, s10
	ds_read_b128 v[172:175], v179 offset:49152
	ds_read_b128 v[180:183], v179 offset:50176
	ds_read_b128 v[184:187], v179 offset:51200
	ds_read_b128 v[188:191], v179 offset:52224
	ds_read_b128 v[192:195], v179 offset:53248
	ds_read_b128 v[200:203], v179 offset:54272
	ds_read_b128 v[206:209], v179 offset:55296
	ds_read_b128 v[210:213], v179 offset:56320
	global_load_lds_dwordx4 v[176:177], off
	s_add_i32 m0, s10, 0x2000
	s_add_u32 s8, s8, 0x40080
	v_lshl_add_u64 v[176:177], v[196:197], 0, s[36:37]
	s_addc_u32 s9, s9, 0
	s_add_i32 s10, s75, s13
	global_load_lds_dwordx4 v[176:177], off
	v_lshl_add_u64 v[176:177], s[8:9], 0, v[140:141]
	s_mov_b32 m0, s10
	s_nop 0
	global_load_lds_dwordx4 v[176:177], off
	v_lshl_add_u64 v[176:177], s[8:9], 0, v[158:159]
	s_add_i32 m0, s10, 0x2000
	s_nop 0
	global_load_lds_dwordx4 v[176:177], off
	v_lshl_add_u64 v[176:177], v[198:199], 0, s[36:37]
	s_mov_b32 m0, s29
	s_nop 0
	global_load_lds_dwordx4 v[176:177], off
	v_lshl_add_u64 v[176:177], v[204:205], 0, s[36:37]
	s_mov_b32 m0, s42
	s_nop 0
	global_load_lds_dwordx4 v[176:177], off
	s_waitcnt vmcnt(8)
	s_waitcnt lgkmcnt(0)
	s_barrier
	s_setprio 1
	s_waitcnt lgkmcnt(0)
	v_mfma_f32_16x16x32_bf16 v[60:63], v[128:131], v[172:175], v[60:63]
	v_mfma_f32_16x16x32_bf16 v[56:59], v[136:139], v[172:175], v[56:59]
	v_mfma_f32_16x16x32_bf16 v[44:47], v[128:131], v[184:187], v[44:47]
	v_mfma_f32_16x16x32_bf16 v[40:43], v[136:139], v[184:187], v[40:43]
	v_mfma_f32_16x16x32_bf16 v[28:31], v[128:131], v[192:195], v[28:31]
	v_mfma_f32_16x16x32_bf16 v[24:27], v[136:139], v[192:195], v[24:27]
	v_mfma_f32_16x16x32_bf16 v[12:15], v[128:131], v[206:209], v[12:15]
	v_mfma_f32_16x16x32_bf16 v[8:11], v[136:139], v[206:209], v[8:11]
	v_mfma_f32_16x16x32_bf16 v[60:63], v[132:135], v[180:183], v[60:63]
	v_mfma_f32_16x16x32_bf16 v[56:59], v[142:145], v[180:183], v[56:59]
	v_mfma_f32_16x16x32_bf16 v[44:47], v[132:135], v[188:191], v[44:47]
	v_mfma_f32_16x16x32_bf16 v[40:43], v[142:145], v[188:191], v[40:43]
	v_mfma_f32_16x16x32_bf16 v[28:31], v[132:135], v[200:203], v[28:31]
	v_mfma_f32_16x16x32_bf16 v[24:27], v[142:145], v[200:203], v[24:27]
	v_mfma_f32_16x16x32_bf16 v[12:15], v[132:135], v[210:213], v[12:15]
	v_mfma_f32_16x16x32_bf16 v[8:11], v[142:145], v[210:213], v[8:11]
	s_setprio 0
	s_setprio 1
	v_mfma_f32_16x16x32_bf16 v[52:55], v[146:149], v[172:175], v[52:55]
	v_mfma_f32_16x16x32_bf16 v[48:51], v[154:157], v[172:175], v[48:51]
	v_mfma_f32_16x16x32_bf16 v[36:39], v[146:149], v[184:187], v[36:39]
	v_mfma_f32_16x16x32_bf16 v[32:35], v[154:157], v[184:187], v[32:35]
	v_mfma_f32_16x16x32_bf16 v[20:23], v[146:149], v[192:195], v[20:23]
	v_mfma_f32_16x16x32_bf16 v[16:19], v[154:157], v[192:195], v[16:19]
	v_mfma_f32_16x16x32_bf16 v[4:7], v[146:149], v[206:209], v[4:7]
	v_mfma_f32_16x16x32_bf16 v[0:3], v[154:157], v[206:209], v[0:3]
	v_mfma_f32_16x16x32_bf16 v[52:55], v[150:153], v[180:183], v[52:55]
	v_mfma_f32_16x16x32_bf16 v[48:51], v[168:171], v[180:183], v[48:51]
	v_mfma_f32_16x16x32_bf16 v[36:39], v[150:153], v[188:191], v[36:39]
	v_mfma_f32_16x16x32_bf16 v[32:35], v[168:171], v[188:191], v[32:35]
	v_mfma_f32_16x16x32_bf16 v[20:23], v[150:153], v[200:203], v[20:23]
	v_mfma_f32_16x16x32_bf16 v[16:19], v[168:171], v[200:203], v[16:19]
	v_mfma_f32_16x16x32_bf16 v[4:7], v[150:153], v[210:213], v[4:7]
	v_mfma_f32_16x16x32_bf16 v[0:3], v[168:171], v[210:213], v[0:3]
	s_setprio 0
	s_add_i32 s74, s74, 2
	s_add_u32 s6, s6, 0x100
	s_addc_u32 s7, s7, 0
	s_add_u32 s60, s60, 0x100
	s_addc_u32 s61, s61, 0
	s_cmp_gt_u32 s74, 13
	s_cbranch_scc0 .LBB0_147
	s_and_b64 vcc, exec, s[50:51]
	s_cbranch_vccz .LBB0_150
	s_barrier

.LBB0_233:
	s_ashr_i32 s53, s52, 31
	s_lshl_b64 s[4:5], s[52:53], 19
	s_add_u32 s54, s68, s4
	s_addc_u32 s55, s69, s5
	s_and_b64 s[4:5], s[40:41], exec
	s_cselect_b32 s4, s55, s7
	s_cselect_b32 s5, s54, s6
	s_ashr_i32 s42, s52, 4
	s_ashr_i32 s51, s50, 31
	s_ashr_i32 s43, s42, 31
	s_lshl_b64 s[10:11], s[50:51], 19
	s_lshl_b64 s[42:43], s[42:43], 21
	s_add_u32 s10, s81, s10
	s_addc_u32 s11, s25, s11
	s_add_u32 s56, s10, s42
	s_addc_u32 s57, s11, s43
	s_and_b64 s[10:11], s[40:41], exec
	s_cselect_b32 s24, s57, s9
	s_cselect_b32 s42, s56, s8
	s_add_u32 s6, s6, 0x40080
	s_addc_u32 s7, s7, 0
	s_add_u32 s43, s8, 0x100
	v_mov_b32_e32 v0, 0
	v_mov_b32_e32 v251, 0x260
	v_mov_b32_e32 v222, 0x3e124925
	v_mov_b32_e32 v221, 0x3e2aaaab
	v_mov_b32_e32 v220, 0x3e4ccccd
	v_mov_b32_e32 v219, 0x3e800000
	v_mov_b32_e32 v218, 0x3eaaaaab
	s_addc_u32 s51, s9, 0
	s_mov_b32 s53, -2
	v_mov_b32_e32 v1, v0
	v_mov_b32_e32 v2, v0
	v_mov_b32_e32 v3, v0
	v_mov_b32_e32 v4, v0
	v_mov_b32_e32 v5, v0
	v_mov_b32_e32 v6, v0
	v_mov_b32_e32 v7, v0
	v_mov_b32_e32 v16, v0
	v_mov_b32_e32 v17, v0
	v_mov_b32_e32 v18, v0
	v_mov_b32_e32 v19, v0
	v_mov_b32_e32 v20, v0
	v_mov_b32_e32 v21, v0
	v_mov_b32_e32 v22, v0
	v_mov_b32_e32 v23, v0
	v_mov_b32_e32 v32, v0
	v_mov_b32_e32 v33, v0
	v_mov_b32_e32 v34, v0
	v_mov_b32_e32 v35, v0
	v_mov_b32_e32 v36, v0
	v_mov_b32_e32 v37, v0
	v_mov_b32_e32 v38, v0
	v_mov_b32_e32 v39, v0
	v_mov_b32_e32 v48, v0
	v_mov_b32_e32 v49, v0
	v_mov_b32_e32 v50, v0
	v_mov_b32_e32 v51, v0
	v_mov_b32_e32 v52, v0
	v_mov_b32_e32 v53, v0
	v_mov_b32_e32 v54, v0
	v_mov_b32_e32 v55, v0
	v_mov_b32_e32 v8, v0
	v_mov_b32_e32 v9, v0
	v_mov_b32_e32 v10, v0
	v_mov_b32_e32 v11, v0
	v_mov_b32_e32 v12, v0
	v_mov_b32_e32 v13, v0
	v_mov_b32_e32 v14, v0
	v_mov_b32_e32 v15, v0
	v_mov_b32_e32 v24, v0
	v_mov_b32_e32 v25, v0
	v_mov_b32_e32 v26, v0
	v_mov_b32_e32 v27, v0
	v_mov_b32_e32 v28, v0
	v_mov_b32_e32 v29, v0
	v_mov_b32_e32 v30, v0
	v_mov_b32_e32 v31, v0
	v_mov_b32_e32 v40, v0
	v_mov_b32_e32 v41, v0
	v_mov_b32_e32 v42, v0
	v_mov_b32_e32 v43, v0
	v_mov_b32_e32 v44, v0
	v_mov_b32_e32 v45, v0
	v_mov_b32_e32 v46, v0
	v_mov_b32_e32 v47, v0
	v_mov_b32_e32 v56, v0
	v_mov_b32_e32 v57, v0
	v_mov_b32_e32 v58, v0
	v_mov_b32_e32 v59, v0
	v_mov_b32_e32 v60, v0
	v_mov_b32_e32 v61, v0
	v_mov_b32_e32 v62, v0
	v_mov_b32_e32 v63, v0
	v_mov_b32_e32 v64, v0
	v_mov_b32_e32 v65, v0
	v_mov_b32_e32 v66, v0
	v_mov_b32_e32 v67, v0
	v_mov_b32_e32 v68, v0
	v_mov_b32_e32 v69, v0
	v_mov_b32_e32 v70, v0
	v_mov_b32_e32 v71, v0
	v_mov_b32_e32 v80, v0
	v_mov_b32_e32 v81, v0
	v_mov_b32_e32 v82, v0
	v_mov_b32_e32 v83, v0
	v_mov_b32_e32 v84, v0
	v_mov_b32_e32 v85, v0
	v_mov_b32_e32 v86, v0
	v_mov_b32_e32 v87, v0
	v_mov_b32_e32 v96, v0
	v_mov_b32_e32 v97, v0
	v_mov_b32_e32 v98, v0
	v_mov_b32_e32 v99, v0
	v_mov_b32_e32 v100, v0
	v_mov_b32_e32 v101, v0
	v_mov_b32_e32 v102, v0
	v_mov_b32_e32 v103, v0
	v_mov_b32_e32 v112, v0
	v_mov_b32_e32 v113, v0
	v_mov_b32_e32 v114, v0
	v_mov_b32_e32 v115, v0
	v_mov_b32_e32 v116, v0
	v_mov_b32_e32 v117, v0
	v_mov_b32_e32 v118, v0
	v_mov_b32_e32 v119, v0
	v_mov_b32_e32 v72, v0
	v_mov_b32_e32 v73, v0
	v_mov_b32_e32 v74, v0
	v_mov_b32_e32 v75, v0
	v_mov_b32_e32 v76, v0
	v_mov_b32_e32 v77, v0
	v_mov_b32_e32 v78, v0
	v_mov_b32_e32 v79, v0
	v_mov_b32_e32 v88, v0
	v_mov_b32_e32 v89, v0
	v_mov_b32_e32 v90, v0
	v_mov_b32_e32 v91, v0
	v_mov_b32_e32 v92, v0
	v_mov_b32_e32 v93, v0
	v_mov_b32_e32 v94, v0
	v_mov_b32_e32 v95, v0
	v_mov_b32_e32 v104, v0
	v_mov_b32_e32 v105, v0
	v_mov_b32_e32 v106, v0
	v_mov_b32_e32 v107, v0
	v_mov_b32_e32 v108, v0
	v_mov_b32_e32 v109, v0
	v_mov_b32_e32 v110, v0
	v_mov_b32_e32 v111, v0
	v_mov_b32_e32 v120, v0
	v_mov_b32_e32 v121, v0
	v_mov_b32_e32 v122, v0
	v_mov_b32_e32 v123, v0
	v_mov_b32_e32 v124, v0
	v_mov_b32_e32 v125, v0
	v_mov_b32_e32 v126, v0
	v_mov_b32_e32 v127, v0
	s_branch .Lrot_234

.Lrot_234:
	s_add_u32 s8, s6, 0xfffc0080
	s_addc_u32 s9, s7, -1
	s_add_i32 s35, 0, 0x10000
	s_cmp_eq_u32 s53, 12
	s_cselect_b32 s11, s4, s9
	s_cselect_b32 s10, s5, s8
	v_add_u32_e32 v140, s35, v206
	s_cselect_b32 s9, s24, s51
	s_cselect_b32 s8, s42, s43
	s_add_i32 s76, 0, 0x14000
	ds_read_b128 v[142:145], v140
	ds_read_b128 v[146:149], v140 offset:1024
	ds_read_b128 v[150:153], v140 offset:2048
	ds_read_b128 v[154:157], v140 offset:3072
	v_add_u32_e32 v140, s76, v206
	ds_read_b128 v[158:161], v140
	ds_read_b128 v[162:165], v140 offset:1024
	ds_read_b128 v[166:169], v140 offset:2048
	ds_read_b128 v[170:173], v140 offset:3072
	v_lshl_add_u64 v[198:199], s[6:7], 0, v[136:137]
	s_add_i32 m0, s15, 0xc000
	ds_read_b128 v[174:177], v207
	ds_read_b128 v[178:181], v207 offset:1024
	ds_read_b128 v[182:185], v207 offset:2048
	ds_read_b128 v[186:189], v207 offset:3072
	ds_read_b128 v[190:193], v207 offset:4096
	ds_read_b128 v[194:197], v207 offset:5120
	ds_read_b128 v[200:203], v207 offset:6144
	ds_read_b128 v[208:211], v207 offset:7168
	global_load_lds_dwordx4 v[198:199], off
	v_lshl_add_u64 v[198:199], s[6:7], 0, v[138:139]
	s_add_i32 m0, s15, 0xe000
	s_nop 0
	global_load_lds_dwordx4 v[198:199], off
	s_waitcnt vmcnt(8)
	s_waitcnt lgkmcnt(0)
	s_barrier
	s_setprio 1
	s_waitcnt lgkmcnt(0)
	v_mfma_f32_16x16x32_bf16 v[124:127], v[142:145], v[174:177], v[124:127]
	v_mfma_f32_16x16x32_bf16 v[120:123], v[150:153], v[174:177], v[120:123]
	v_mfma_f32_16x16x32_bf16 v[108:111], v[142:145], v[182:185], v[108:111]
	v_mfma_f32_16x16x32_bf16 v[104:107], v[150:153], v[182:185], v[104:107]
	v_mfma_f32_16x16x32_bf16 v[92:95], v[142:145], v[190:193], v[92:95]
	v_mfma_f32_16x16x32_bf16 v[88:91], v[150:153], v[190:193], v[88:91]
	v_mfma_f32_16x16x32_bf16 v[76:79], v[142:145], v[200:203], v[76:79]
	v_mfma_f32_16x16x32_bf16 v[72:75], v[150:153], v[200:203], v[72:75]
	v_mfma_f32_16x16x32_bf16 v[124:127], v[146:149], v[178:181], v[124:127]
	v_mfma_f32_16x16x32_bf16 v[120:123], v[154:157], v[178:181], v[120:123]
	v_mfma_f32_16x16x32_bf16 v[108:111], v[146:149], v[186:189], v[108:111]
	v_mfma_f32_16x16x32_bf16 v[104:107], v[154:157], v[186:189], v[104:107]
	v_mfma_f32_16x16x32_bf16 v[92:95], v[146:149], v[194:197], v[92:95]
	v_mfma_f32_16x16x32_bf16 v[88:91], v[154:157], v[194:197], v[88:91]
	v_mfma_f32_16x16x32_bf16 v[76:79], v[146:149], v[208:211], v[76:79]
	v_mfma_f32_16x16x32_bf16 v[72:75], v[154:157], v[208:211], v[72:75]
	s_setprio 0
	s_setprio 1
	v_mfma_f32_16x16x32_bf16 v[116:119], v[158:161], v[174:177], v[116:119]
	v_mfma_f32_16x16x32_bf16 v[112:115], v[166:169], v[174:177], v[112:115]
	v_mfma_f32_16x16x32_bf16 v[100:103], v[158:161], v[182:185], v[100:103]
	v_mfma_f32_16x16x32_bf16 v[96:99], v[166:169], v[182:185], v[96:99]
	v_mfma_f32_16x16x32_bf16 v[84:87], v[158:161], v[190:193], v[84:87]
	v_mfma_f32_16x16x32_bf16 v[80:83], v[166:169], v[190:193], v[80:83]
	v_mfma_f32_16x16x32_bf16 v[68:71], v[158:161], v[200:203], v[68:71]
	v_mfma_f32_16x16x32_bf16 v[64:67], v[166:169], v[200:203], v[64:67]
	v_mfma_f32_16x16x32_bf16 v[116:119], v[162:165], v[178:181], v[116:119]
	v_mfma_f32_16x16x32_bf16 v[112:115], v[170:173], v[178:181], v[112:115]
	v_mfma_f32_16x16x32_bf16 v[100:103], v[162:165], v[186:189], v[100:103]
	v_mfma_f32_16x16x32_bf16 v[96:99], v[170:173], v[186:189], v[96:99]
	v_mfma_f32_16x16x32_bf16 v[84:87], v[162:165], v[194:197], v[84:87]
	v_mfma_f32_16x16x32_bf16 v[80:83], v[170:173], v[194:197], v[80:83]
	v_mfma_f32_16x16x32_bf16 v[68:71], v[162:165], v[208:211], v[68:71]
	v_mfma_f32_16x16x32_bf16 v[64:67], v[170:173], v[208:211], v[64:67]
	s_setprio 0
	s_barrier
	s_add_i32 s35, s35, s13
	v_lshl_add_u64 v[198:199], s[8:9], 0, v[132:133]
	s_mov_b32 m0, s35
	ds_read_b128 v[174:177], v207 offset:16384
	ds_read_b128 v[178:181], v207 offset:17408
	ds_read_b128 v[182:185], v207 offset:18432
	ds_read_b128 v[186:189], v207 offset:19456
	ds_read_b128 v[190:193], v207 offset:20480
	ds_read_b128 v[194:197], v207 offset:21504
	ds_read_b128 v[200:203], v207 offset:22528
	ds_read_b128 v[208:211], v207 offset:23552
	global_load_lds_dwordx4 v[198:199], off
	s_add_i32 m0, s35, 0x2000
	s_add_u32 s60, s8, 0x40000
	v_lshl_add_u64 v[204:205], s[8:9], 0, v[128:129]
	s_addc_u32 s61, s9, 0
	s_add_i32 s35, s76, s13
	global_load_lds_dwordx4 v[204:205], off
	v_lshl_add_u64 v[212:213], s[60:61], 0, v[132:133]
	s_mov_b32 m0, s35
	v_lshl_add_u64 v[214:215], s[10:11], 0, v[130:131]
	global_load_lds_dwordx4 v[212:213], off
	v_lshl_add_u64 v[212:213], s[60:61], 0, v[128:129]
	s_add_i32 m0, s35, 0x2000
	s_nop 0
	global_load_lds_dwordx4 v[212:213], off
	v_lshl_add_u64 v[212:213], s[10:11], 0, v[134:135]
	s_mov_b32 m0, s15
	s_nop 0
	global_load_lds_dwordx4 v[212:213], off
	s_mov_b32 m0, s26
	s_nop 0
	global_load_lds_dwordx4 v[214:215], off
	s_waitcnt vmcnt(8)
	s_waitcnt lgkmcnt(0)
	s_barrier
	s_setprio 1
	s_waitcnt lgkmcnt(0)
	v_mfma_f32_16x16x32_bf16 v[60:63], v[142:145], v[174:177], v[60:63]
	v_mfma_f32_16x16x32_bf16 v[56:59], v[150:153], v[174:177], v[56:59]
	v_mfma_f32_16x16x32_bf16 v[44:47], v[142:145], v[182:185], v[44:47]
	v_mfma_f32_16x16x32_bf16 v[40:43], v[150:153], v[182:185], v[40:43]
	v_mfma_f32_16x16x32_bf16 v[28:31], v[142:145], v[190:193], v[28:31]
	v_mfma_f32_16x16x32_bf16 v[24:27], v[150:153], v[190:193], v[24:27]
	v_mfma_f32_16x16x32_bf16 v[12:15], v[142:145], v[200:203], v[12:15]
	v_mfma_f32_16x16x32_bf16 v[8:11], v[150:153], v[200:203], v[8:11]
	v_mfma_f32_16x16x32_bf16 v[60:63], v[146:149], v[178:181], v[60:63]
	v_mfma_f32_16x16x32_bf16 v[56:59], v[154:157], v[178:181], v[56:59]
	v_mfma_f32_16x16x32_bf16 v[44:47], v[146:149], v[186:189], v[44:47]
	v_mfma_f32_16x16x32_bf16 v[40:43], v[154:157], v[186:189], v[40:43]
	v_mfma_f32_16x16x32_bf16 v[28:31], v[146:149], v[194:197], v[28:31]
	v_mfma_f32_16x16x32_bf16 v[24:27], v[154:157], v[194:197], v[24:27]
	v_mfma_f32_16x16x32_bf16 v[12:15], v[146:149], v[208:211], v[12:15]
	v_mfma_f32_16x16x32_bf16 v[8:11], v[154:157], v[208:211], v[8:11]
	s_setprio 0
	s_setprio 1
	v_mfma_f32_16x16x32_bf16 v[52:55], v[158:161], v[174:177], v[52:55]
	v_mfma_f32_16x16x32_bf16 v[48:51], v[166:169], v[174:177], v[48:51]
	v_mfma_f32_16x16x32_bf16 v[36:39], v[158:161], v[182:185], v[36:39]
	v_mfma_f32_16x16x32_bf16 v[32:35], v[166:169], v[182:185], v[32:35]
	v_mfma_f32_16x16x32_bf16 v[20:23], v[158:161], v[190:193], v[20:23]
	v_mfma_f32_16x16x32_bf16 v[16:19], v[166:169], v[190:193], v[16:19]
	v_mfma_f32_16x16x32_bf16 v[4:7], v[158:161], v[200:203], v[4:7]
	v_mfma_f32_16x16x32_bf16 v[0:3], v[166:169], v[200:203], v[0:3]
	v_mfma_f32_16x16x32_bf16 v[52:55], v[162:165], v[178:181], v[52:55]
	v_mfma_f32_16x16x32_bf16 v[48:51], v[170:173], v[178:181], v[48:51]
	v_mfma_f32_16x16x32_bf16 v[36:39], v[162:165], v[186:189], v[36:39]
	v_mfma_f32_16x16x32_bf16 v[32:35], v[170:173], v[186:189], v[32:35]
	v_mfma_f32_16x16x32_bf16 v[20:23], v[162:165], v[194:197], v[20:23]
	v_mfma_f32_16x16x32_bf16 v[16:19], v[170:173], v[194:197], v[16:19]
	v_mfma_f32_16x16x32_bf16 v[4:7], v[162:165], v[208:211], v[4:7]
	v_mfma_f32_16x16x32_bf16 v[0:3], v[170:173], v[208:211], v[0:3]
	s_setprio 0
	s_barrier
	s_add_i32 s35, 0, 0x18000
	v_add_u32_e32 v140, s35, v206
	s_add_i32 s60, 0, 0x1c000
	ds_read_b128 v[142:145], v140
	ds_read_b128 v[146:149], v140 offset:1024
	ds_read_b128 v[150:153], v140 offset:2048
	ds_read_b128 v[154:157], v140 offset:3072
	v_add_u32_e32 v140, s60, v206
	ds_read_b128 v[158:161], v140
	ds_read_b128 v[162:165], v140 offset:1024
	ds_read_b128 v[166:169], v140 offset:2048
	ds_read_b128 v[170:173], v140 offset:3072
	s_add_u32 s10, s10, 0x40000
	s_addc_u32 s11, s11, 0
	s_mov_b32 m0, s27
	v_lshl_add_u64 v[216:217], s[10:11], 0, v[134:135]
	ds_read_b128 v[174:177], v207 offset:32768
	ds_read_b128 v[178:181], v207 offset:33792
	ds_read_b128 v[182:185], v207 offset:34816
	ds_read_b128 v[186:189], v207 offset:35840
	ds_read_b128 v[190:193], v207 offset:36864
	ds_read_b128 v[194:197], v207 offset:37888
	ds_read_b128 v[200:203], v207 offset:38912
	ds_read_b128 v[208:211], v207 offset:39936
	global_load_lds_dwordx4 v[216:217], off
	v_lshl_add_u64 v[216:217], s[10:11], 0, v[130:131]
	s_mov_b32 m0, s28
	s_nop 0
	global_load_lds_dwordx4 v[216:217], off
	s_waitcnt vmcnt(8)
	s_waitcnt lgkmcnt(0)
	s_barrier
	s_setprio 1
	s_waitcnt lgkmcnt(0)
	v_mfma_f32_16x16x32_bf16 v[124:127], v[142:145], v[174:177], v[124:127]
	v_mfma_f32_16x16x32_bf16 v[120:123], v[150:153], v[174:177], v[120:123]
	v_mfma_f32_16x16x32_bf16 v[108:111], v[142:145], v[182:185], v[108:111]
	v_mfma_f32_16x16x32_bf16 v[104:107], v[150:153], v[182:185], v[104:107]
	v_mfma_f32_16x16x32_bf16 v[92:95], v[142:145], v[190:193], v[92:95]
	v_mfma_f32_16x16x32_bf16 v[88:91], v[150:153], v[190:193], v[88:91]
	v_mfma_f32_16x16x32_bf16 v[76:79], v[142:145], v[200:203], v[76:79]
	v_mfma_f32_16x16x32_bf16 v[72:75], v[150:153], v[200:203], v[72:75]
	v_mfma_f32_16x16x32_bf16 v[124:127], v[146:149], v[178:181], v[124:127]
	v_mfma_f32_16x16x32_bf16 v[120:123], v[154:157], v[178:181], v[120:123]
	v_mfma_f32_16x16x32_bf16 v[108:111], v[146:149], v[186:189], v[108:111]
	v_mfma_f32_16x16x32_bf16 v[104:107], v[154:157], v[186:189], v[104:107]
	v_mfma_f32_16x16x32_bf16 v[92:95], v[146:149], v[194:197], v[92:95]
	v_mfma_f32_16x16x32_bf16 v[88:91], v[154:157], v[194:197], v[88:91]
	v_mfma_f32_16x16x32_bf16 v[76:79], v[146:149], v[208:211], v[76:79]
	v_mfma_f32_16x16x32_bf16 v[72:75], v[154:157], v[208:211], v[72:75]
	s_setprio 0
	s_setprio 1
	v_mfma_f32_16x16x32_bf16 v[116:119], v[158:161], v[174:177], v[116:119]
	v_mfma_f32_16x16x32_bf16 v[112:115], v[166:169], v[174:177], v[112:115]
	v_mfma_f32_16x16x32_bf16 v[100:103], v[158:161], v[182:185], v[100:103]
	v_mfma_f32_16x16x32_bf16 v[96:99], v[166:169], v[182:185], v[96:99]
	v_mfma_f32_16x16x32_bf16 v[84:87], v[158:161], v[190:193], v[84:87]
	v_mfma_f32_16x16x32_bf16 v[80:83], v[166:169], v[190:193], v[80:83]
	v_mfma_f32_16x16x32_bf16 v[68:71], v[158:161], v[200:203], v[68:71]
	v_mfma_f32_16x16x32_bf16 v[64:67], v[166:169], v[200:203], v[64:67]
	v_mfma_f32_16x16x32_bf16 v[116:119], v[162:165], v[178:181], v[116:119]
	v_mfma_f32_16x16x32_bf16 v[112:115], v[170:173], v[178:181], v[112:115]
	v_mfma_f32_16x16x32_bf16 v[100:103], v[162:165], v[186:189], v[100:103]
	v_mfma_f32_16x16x32_bf16 v[96:99], v[170:173], v[186:189], v[96:99]
	v_mfma_f32_16x16x32_bf16 v[84:87], v[162:165], v[194:197], v[84:87]
	v_mfma_f32_16x16x32_bf16 v[80:83], v[170:173], v[194:197], v[80:83]
	v_mfma_f32_16x16x32_bf16 v[68:71], v[162:165], v[208:211], v[68:71]
	v_mfma_f32_16x16x32_bf16 v[64:67], v[170:173], v[208:211], v[64:67]
	s_setprio 0
	s_barrier
	s_add_i32 s10, s35, s13
	v_lshl_add_u64 v[198:199], v[198:199], 0, s[36:37]
	s_mov_b32 m0, s10
	ds_read_b128 v[174:177], v207 offset:49152
	ds_read_b128 v[178:181], v207 offset:50176
	ds_read_b128 v[182:185], v207 offset:51200
	ds_read_b128 v[186:189], v207 offset:52224
	ds_read_b128 v[190:193], v207 offset:53248
	ds_read_b128 v[194:197], v207 offset:54272
	ds_read_b128 v[200:203], v207 offset:55296
	ds_read_b128 v[208:211], v207 offset:56320
	global_load_lds_dwordx4 v[198:199], off
	s_add_i32 m0, s10, 0x2000
	s_add_u32 s8, s8, 0x40080
	v_lshl_add_u64 v[198:199], v[204:205], 0, s[36:37]
	s_addc_u32 s9, s9, 0
	s_add_i32 s10, s60, s13
	global_load_lds_dwordx4 v[198:199], off
	v_lshl_add_u64 v[198:199], s[8:9], 0, v[132:133]
	s_mov_b32 m0, s10
	s_nop 0
	global_load_lds_dwordx4 v[198:199], off
	v_lshl_add_u64 v[198:199], s[8:9], 0, v[128:129]
	s_add_i32 m0, s10, 0x2000
	s_nop 0
	global_load_lds_dwordx4 v[198:199], off
	v_lshl_add_u64 v[198:199], v[212:213], 0, s[36:37]
	s_mov_b32 m0, s29
	s_nop 0
	global_load_lds_dwordx4 v[198:199], off
	v_lshl_add_u64 v[198:199], v[214:215], 0, s[36:37]
	s_mov_b32 m0, s38
	s_nop 0
	global_load_lds_dwordx4 v[198:199], off
	s_waitcnt vmcnt(8)
	s_waitcnt lgkmcnt(0)
	s_barrier
	s_setprio 1
	s_waitcnt lgkmcnt(0)
	v_mfma_f32_16x16x32_bf16 v[60:63], v[142:145], v[174:177], v[60:63]
	v_mfma_f32_16x16x32_bf16 v[56:59], v[150:153], v[174:177], v[56:59]
	v_mfma_f32_16x16x32_bf16 v[44:47], v[142:145], v[182:185], v[44:47]
	v_mfma_f32_16x16x32_bf16 v[40:43], v[150:153], v[182:185], v[40:43]
	v_mfma_f32_16x16x32_bf16 v[28:31], v[142:145], v[190:193], v[28:31]
	v_mfma_f32_16x16x32_bf16 v[24:27], v[150:153], v[190:193], v[24:27]
	v_mfma_f32_16x16x32_bf16 v[12:15], v[142:145], v[200:203], v[12:15]
	v_mfma_f32_16x16x32_bf16 v[8:11], v[150:153], v[200:203], v[8:11]
	v_mfma_f32_16x16x32_bf16 v[60:63], v[146:149], v[178:181], v[60:63]
	v_mfma_f32_16x16x32_bf16 v[56:59], v[154:157], v[178:181], v[56:59]
	v_mfma_f32_16x16x32_bf16 v[44:47], v[146:149], v[186:189], v[44:47]
	v_mfma_f32_16x16x32_bf16 v[40:43], v[154:157], v[186:189], v[40:43]
	v_mfma_f32_16x16x32_bf16 v[28:31], v[146:149], v[194:197], v[28:31]
	v_mfma_f32_16x16x32_bf16 v[24:27], v[154:157], v[194:197], v[24:27]
	v_mfma_f32_16x16x32_bf16 v[12:15], v[146:149], v[208:211], v[12:15]
	v_mfma_f32_16x16x32_bf16 v[8:11], v[154:157], v[208:211], v[8:11]
	s_setprio 0
	s_setprio 1
	v_mfma_f32_16x16x32_bf16 v[52:55], v[158:161], v[174:177], v[52:55]
	v_mfma_f32_16x16x32_bf16 v[48:51], v[166:169], v[174:177], v[48:51]
	v_mfma_f32_16x16x32_bf16 v[36:39], v[158:161], v[182:185], v[36:39]
	v_mfma_f32_16x16x32_bf16 v[32:35], v[166:169], v[182:185], v[32:35]
	v_mfma_f32_16x16x32_bf16 v[20:23], v[158:161], v[190:193], v[20:23]
	v_mfma_f32_16x16x32_bf16 v[16:19], v[166:169], v[190:193], v[16:19]
	v_mfma_f32_16x16x32_bf16 v[4:7], v[158:161], v[200:203], v[4:7]
	v_mfma_f32_16x16x32_bf16 v[0:3], v[166:169], v[200:203], v[0:3]
	v_mfma_f32_16x16x32_bf16 v[52:55], v[162:165], v[178:181], v[52:55]
	v_mfma_f32_16x16x32_bf16 v[48:51], v[170:173], v[178:181], v[48:51]
	v_mfma_f32_16x16x32_bf16 v[36:39], v[162:165], v[186:189], v[36:39]
	v_mfma_f32_16x16x32_bf16 v[32:35], v[170:173], v[186:189], v[32:35]
	v_mfma_f32_16x16x32_bf16 v[20:23], v[162:165], v[194:197], v[20:23]
	v_mfma_f32_16x16x32_bf16 v[16:19], v[170:173], v[194:197], v[16:19]
	v_mfma_f32_16x16x32_bf16 v[4:7], v[162:165], v[208:211], v[4:7]
	v_mfma_f32_16x16x32_bf16 v[0:3], v[170:173], v[208:211], v[0:3]
	s_setprio 0
	s_add_i32 s53, s53, 2
	s_add_u32 s6, s6, 0x100
	s_addc_u32 s7, s7, 0
	s_add_u32 s43, s43, 0x100
	s_addc_u32 s51, s51, 0
	s_cmp_gt_u32 s53, 13
	s_cbranch_scc0 .LBB0_234
	s_and_b64 vcc, exec, s[48:49]
	s_cbranch_vccz .LBB0_237
	s_barrier

.LBB0_332:
	s_add_u32 s24, s6, 0x100
	s_addc_u32 s38, s7, 0
	s_add_u32 s6, s8, 0x8000
	v_mov_b32_e32 v0, 0
	s_addc_u32 s7, s9, 0
	s_mov_b32 s8, 0
	v_mov_b32_e32 v1, v0
	v_mov_b32_e32 v2, v0
	v_mov_b32_e32 v3, v0
	v_mov_b32_e32 v4, v0
	v_mov_b32_e32 v5, v0
	v_mov_b32_e32 v6, v0
	v_mov_b32_e32 v7, v0
	v_mov_b32_e32 v16, v0
	v_mov_b32_e32 v17, v0
	v_mov_b32_e32 v18, v0
	v_mov_b32_e32 v19, v0
	v_mov_b32_e32 v20, v0
	v_mov_b32_e32 v21, v0
	v_mov_b32_e32 v22, v0
	v_mov_b32_e32 v23, v0
	v_mov_b32_e32 v32, v0
	v_mov_b32_e32 v33, v0
	v_mov_b32_e32 v34, v0
	v_mov_b32_e32 v35, v0
	v_mov_b32_e32 v36, v0
	v_mov_b32_e32 v37, v0
	v_mov_b32_e32 v38, v0
	v_mov_b32_e32 v39, v0
	v_mov_b32_e32 v48, v0
	v_mov_b32_e32 v49, v0
	v_mov_b32_e32 v50, v0
	v_mov_b32_e32 v51, v0
	v_mov_b32_e32 v52, v0
	v_mov_b32_e32 v53, v0
	v_mov_b32_e32 v54, v0
	v_mov_b32_e32 v55, v0
	v_mov_b32_e32 v8, v0
	v_mov_b32_e32 v9, v0
	v_mov_b32_e32 v10, v0
	v_mov_b32_e32 v11, v0
	v_mov_b32_e32 v12, v0
	v_mov_b32_e32 v13, v0
	v_mov_b32_e32 v14, v0
	v_mov_b32_e32 v15, v0
	v_mov_b32_e32 v24, v0
	v_mov_b32_e32 v25, v0
	v_mov_b32_e32 v26, v0
	v_mov_b32_e32 v27, v0
	v_mov_b32_e32 v28, v0
	v_mov_b32_e32 v29, v0
	v_mov_b32_e32 v30, v0
	v_mov_b32_e32 v31, v0
	v_mov_b32_e32 v40, v0
	v_mov_b32_e32 v41, v0
	v_mov_b32_e32 v42, v0
	v_mov_b32_e32 v43, v0
	v_mov_b32_e32 v44, v0
	v_mov_b32_e32 v45, v0
	v_mov_b32_e32 v46, v0
	v_mov_b32_e32 v47, v0
	v_mov_b32_e32 v56, v0
	v_mov_b32_e32 v57, v0
	v_mov_b32_e32 v58, v0
	v_mov_b32_e32 v59, v0
	v_mov_b32_e32 v60, v0
	v_mov_b32_e32 v61, v0
	v_mov_b32_e32 v62, v0
	v_mov_b32_e32 v63, v0
	v_mov_b32_e32 v64, v0
	v_mov_b32_e32 v65, v0
	v_mov_b32_e32 v66, v0
	v_mov_b32_e32 v67, v0
	v_mov_b32_e32 v68, v0
	v_mov_b32_e32 v69, v0
	v_mov_b32_e32 v70, v0
	v_mov_b32_e32 v71, v0
	v_mov_b32_e32 v80, v0
	v_mov_b32_e32 v81, v0
	v_mov_b32_e32 v82, v0
	v_mov_b32_e32 v83, v0
	v_mov_b32_e32 v84, v0
	v_mov_b32_e32 v85, v0
	v_mov_b32_e32 v86, v0
	v_mov_b32_e32 v87, v0
	v_mov_b32_e32 v96, v0
	v_mov_b32_e32 v97, v0
	v_mov_b32_e32 v98, v0
	v_mov_b32_e32 v99, v0
	v_mov_b32_e32 v100, v0
	v_mov_b32_e32 v101, v0
	v_mov_b32_e32 v102, v0
	v_mov_b32_e32 v103, v0
	v_mov_b32_e32 v112, v0
	v_mov_b32_e32 v113, v0
	v_mov_b32_e32 v114, v0
	v_mov_b32_e32 v115, v0
	v_mov_b32_e32 v116, v0
	v_mov_b32_e32 v117, v0
	v_mov_b32_e32 v118, v0
	v_mov_b32_e32 v119, v0
	v_mov_b32_e32 v72, v0
	v_mov_b32_e32 v73, v0
	v_mov_b32_e32 v74, v0
	v_mov_b32_e32 v75, v0
	v_mov_b32_e32 v76, v0
	v_mov_b32_e32 v77, v0
	v_mov_b32_e32 v78, v0
	v_mov_b32_e32 v79, v0
	v_mov_b32_e32 v88, v0
	v_mov_b32_e32 v89, v0
	v_mov_b32_e32 v90, v0
	v_mov_b32_e32 v91, v0
	v_mov_b32_e32 v92, v0
	v_mov_b32_e32 v93, v0
	v_mov_b32_e32 v94, v0
	v_mov_b32_e32 v95, v0
	v_mov_b32_e32 v104, v0
	v_mov_b32_e32 v105, v0
	v_mov_b32_e32 v106, v0
	v_mov_b32_e32 v107, v0
	v_mov_b32_e32 v108, v0
	v_mov_b32_e32 v109, v0
	v_mov_b32_e32 v110, v0
	v_mov_b32_e32 v111, v0
	v_mov_b32_e32 v120, v0
	v_mov_b32_e32 v121, v0
	v_mov_b32_e32 v122, v0
	v_mov_b32_e32 v123, v0
	v_mov_b32_e32 v124, v0
	v_mov_b32_e32 v125, v0
	v_mov_b32_e32 v126, v0
	v_mov_b32_e32 v127, v0
	s_branch .Lrot_333

.Lrot_333:
	s_add_i32 s56, s8, 2
	s_add_u32 s9, s6, 0x8000
	s_addc_u32 s10, s7, 0
	s_cmp_eq_u32 s94, s8
	s_cselect_b32 s11, s43, s10
	s_cselect_b32 s10, s42, s9
	s_cselect_b32 s60, s54, s24
	s_cselect_b32 s61, s55, s38
	s_add_u32 s8, s10, 0x8000
	s_addc_u32 s9, s11, 0
	s_add_i32 s35, 0, 0x10000
	s_add_i32 s57, 0, 0x14000
	v_add_u32_e32 v142, s35, v178
	v_add_u32_e32 v168, s57, v178
	ds_read_b128 v[128:131], v142
	ds_read_b128 v[132:135], v142 offset:1024
	ds_read_b128 v[136:139], v142 offset:2048
	ds_read_b128 v[142:145], v142 offset:3072
	ds_read_b128 v[146:149], v168
	ds_read_b128 v[150:153], v168 offset:1024
	ds_read_b128 v[154:157], v168 offset:2048
	ds_read_b128 v[168:171], v168 offset:3072
	v_lshl_add_u64 v[176:177], s[6:7], 0, v[164:165]
	s_add_i32 m0, s75, 0xc000
	ds_read_b128 v[172:175], v179
	ds_read_b128 v[180:183], v179 offset:1024
	ds_read_b128 v[184:187], v179 offset:2048
	ds_read_b128 v[188:191], v179 offset:3072
	ds_read_b128 v[192:195], v179 offset:4096
	ds_read_b128 v[200:203], v179 offset:5120
	ds_read_b128 v[206:209], v179 offset:6144
	ds_read_b128 v[210:213], v179 offset:7168
	global_load_lds_dwordx4 v[176:177], off
	v_lshl_add_u64 v[176:177], s[6:7], 0, v[166:167]
	s_add_i32 m0, s75, 0xe000
	s_nop 0
	global_load_lds_dwordx4 v[176:177], off
	s_waitcnt vmcnt(8)
	s_waitcnt lgkmcnt(0)
	s_barrier
	s_setprio 1
	s_waitcnt lgkmcnt(0)
	v_mfma_f32_16x16x32_bf16 v[124:127], v[128:131], v[172:175], v[124:127]
	v_mfma_f32_16x16x32_bf16 v[120:123], v[136:139], v[172:175], v[120:123]
	v_mfma_f32_16x16x32_bf16 v[108:111], v[128:131], v[184:187], v[108:111]
	v_mfma_f32_16x16x32_bf16 v[104:107], v[136:139], v[184:187], v[104:107]
	v_mfma_f32_16x16x32_bf16 v[92:95], v[128:131], v[192:195], v[92:95]
	v_mfma_f32_16x16x32_bf16 v[88:91], v[136:139], v[192:195], v[88:91]
	v_mfma_f32_16x16x32_bf16 v[76:79], v[128:131], v[206:209], v[76:79]
	v_mfma_f32_16x16x32_bf16 v[72:75], v[136:139], v[206:209], v[72:75]
	v_mfma_f32_16x16x32_bf16 v[124:127], v[132:135], v[180:183], v[124:127]
	v_mfma_f32_16x16x32_bf16 v[120:123], v[142:145], v[180:183], v[120:123]
	v_mfma_f32_16x16x32_bf16 v[108:111], v[132:135], v[188:191], v[108:111]
	v_mfma_f32_16x16x32_bf16 v[104:107], v[142:145], v[188:191], v[104:107]
	v_mfma_f32_16x16x32_bf16 v[92:95], v[132:135], v[200:203], v[92:95]
	v_mfma_f32_16x16x32_bf16 v[88:91], v[142:145], v[200:203], v[88:91]
	v_mfma_f32_16x16x32_bf16 v[76:79], v[132:135], v[210:213], v[76:79]
	v_mfma_f32_16x16x32_bf16 v[72:75], v[142:145], v[210:213], v[72:75]
	s_setprio 0
	s_setprio 1
	v_mfma_f32_16x16x32_bf16 v[116:119], v[146:149], v[172:175], v[116:119]
	v_mfma_f32_16x16x32_bf16 v[112:115], v[154:157], v[172:175], v[112:115]
	v_mfma_f32_16x16x32_bf16 v[100:103], v[146:149], v[184:187], v[100:103]
	v_mfma_f32_16x16x32_bf16 v[96:99], v[154:157], v[184:187], v[96:99]
	v_mfma_f32_16x16x32_bf16 v[84:87], v[146:149], v[192:195], v[84:87]
	v_mfma_f32_16x16x32_bf16 v[80:83], v[154:157], v[192:195], v[80:83]
	v_mfma_f32_16x16x32_bf16 v[68:71], v[146:149], v[206:209], v[68:71]
	v_mfma_f32_16x16x32_bf16 v[64:67], v[154:157], v[206:209], v[64:67]
	v_mfma_f32_16x16x32_bf16 v[116:119], v[150:153], v[180:183], v[116:119]
	v_mfma_f32_16x16x32_bf16 v[112:115], v[168:171], v[180:183], v[112:115]
	v_mfma_f32_16x16x32_bf16 v[100:103], v[150:153], v[188:191], v[100:103]
	v_mfma_f32_16x16x32_bf16 v[96:99], v[168:171], v[188:191], v[96:99]
	v_mfma_f32_16x16x32_bf16 v[84:87], v[150:153], v[200:203], v[84:87]
	v_mfma_f32_16x16x32_bf16 v[80:83], v[168:171], v[200:203], v[80:83]
	v_mfma_f32_16x16x32_bf16 v[68:71], v[150:153], v[210:213], v[68:71]
	v_mfma_f32_16x16x32_bf16 v[64:67], v[168:171], v[210:213], v[64:67]
	s_setprio 0
	s_barrier
	s_add_i32 s35, s35, s74
	v_lshl_add_u64 v[176:177], s[60:61], 0, v[140:141]
	s_mov_b32 m0, s35
	ds_read_b128 v[172:175], v179 offset:16384
	ds_read_b128 v[180:183], v179 offset:17408
	ds_read_b128 v[184:187], v179 offset:18432
	ds_read_b128 v[188:191], v179 offset:19456
	ds_read_b128 v[192:195], v179 offset:20480
	ds_read_b128 v[200:203], v179 offset:21504
	ds_read_b128 v[206:209], v179 offset:22528
	ds_read_b128 v[210:213], v179 offset:23552
	global_load_lds_dwordx4 v[176:177], off
	s_add_i32 m0, s35, 0x2000
	v_lshl_add_u64 v[196:197], s[60:61], 0, v[158:159]
	s_add_u32 s60, s60, s13
	s_addc_u32 s61, s61, 0
	s_add_i32 s35, s57, s74
	global_load_lds_dwordx4 v[196:197], off
	v_lshl_add_u64 v[198:199], s[60:61], 0, v[140:141]
	s_mov_b32 m0, s35
	v_lshl_add_u64 v[204:205], s[60:61], 0, v[158:159]
	global_load_lds_dwordx4 v[198:199], off
	s_add_i32 m0, s35, 0x2000
	v_lshl_add_u64 v[214:215], s[10:11], 0, v[162:163]
	global_load_lds_dwordx4 v[204:205], off
	s_mov_b32 m0, s75
	s_nop 0
	global_load_lds_dwordx4 v[214:215], off
	v_lshl_add_u64 v[214:215], s[10:11], 0, v[160:161]
	s_mov_b32 m0, s26
	s_nop 0
	global_load_lds_dwordx4 v[214:215], off
	s_waitcnt vmcnt(8)
	s_waitcnt lgkmcnt(0)
	s_barrier
	s_setprio 1
	s_waitcnt lgkmcnt(0)
	v_mfma_f32_16x16x32_bf16 v[60:63], v[128:131], v[172:175], v[60:63]
	v_mfma_f32_16x16x32_bf16 v[56:59], v[136:139], v[172:175], v[56:59]
	v_mfma_f32_16x16x32_bf16 v[44:47], v[128:131], v[184:187], v[44:47]
	v_mfma_f32_16x16x32_bf16 v[40:43], v[136:139], v[184:187], v[40:43]
	v_mfma_f32_16x16x32_bf16 v[28:31], v[128:131], v[192:195], v[28:31]
	v_mfma_f32_16x16x32_bf16 v[24:27], v[136:139], v[192:195], v[24:27]
	v_mfma_f32_16x16x32_bf16 v[12:15], v[128:131], v[206:209], v[12:15]
	v_mfma_f32_16x16x32_bf16 v[8:11], v[136:139], v[206:209], v[8:11]
	v_mfma_f32_16x16x32_bf16 v[60:63], v[132:135], v[180:183], v[60:63]
	v_mfma_f32_16x16x32_bf16 v[56:59], v[142:145], v[180:183], v[56:59]
	v_mfma_f32_16x16x32_bf16 v[44:47], v[132:135], v[188:191], v[44:47]
	v_mfma_f32_16x16x32_bf16 v[40:43], v[142:145], v[188:191], v[40:43]
	v_mfma_f32_16x16x32_bf16 v[28:31], v[132:135], v[200:203], v[28:31]
	v_mfma_f32_16x16x32_bf16 v[24:27], v[142:145], v[200:203], v[24:27]
	v_mfma_f32_16x16x32_bf16 v[12:15], v[132:135], v[210:213], v[12:15]
	v_mfma_f32_16x16x32_bf16 v[8:11], v[142:145], v[210:213], v[8:11]
	s_setprio 0
	s_setprio 1
	v_mfma_f32_16x16x32_bf16 v[52:55], v[146:149], v[172:175], v[52:55]
	v_mfma_f32_16x16x32_bf16 v[48:51], v[154:157], v[172:175], v[48:51]
	v_mfma_f32_16x16x32_bf16 v[36:39], v[146:149], v[184:187], v[36:39]
	v_mfma_f32_16x16x32_bf16 v[32:35], v[154:157], v[184:187], v[32:35]
	v_mfma_f32_16x16x32_bf16 v[20:23], v[146:149], v[192:195], v[20:23]
	v_mfma_f32_16x16x32_bf16 v[16:19], v[154:157], v[192:195], v[16:19]
	v_mfma_f32_16x16x32_bf16 v[4:7], v[146:149], v[206:209], v[4:7]
	v_mfma_f32_16x16x32_bf16 v[0:3], v[154:157], v[206:209], v[0:3]
	v_mfma_f32_16x16x32_bf16 v[52:55], v[150:153], v[180:183], v[52:55]
	v_mfma_f32_16x16x32_bf16 v[48:51], v[168:171], v[180:183], v[48:51]
	v_mfma_f32_16x16x32_bf16 v[36:39], v[150:153], v[188:191], v[36:39]
	v_mfma_f32_16x16x32_bf16 v[32:35], v[168:171], v[188:191], v[32:35]
	v_mfma_f32_16x16x32_bf16 v[20:23], v[150:153], v[200:203], v[20:23]
	v_mfma_f32_16x16x32_bf16 v[16:19], v[168:171], v[200:203], v[16:19]
	v_mfma_f32_16x16x32_bf16 v[4:7], v[150:153], v[210:213], v[4:7]
	v_mfma_f32_16x16x32_bf16 v[0:3], v[168:171], v[210:213], v[0:3]
	s_setprio 0
	s_barrier
	s_add_i32 s35, 0, 0x18000
	s_add_i32 s57, 0, 0x1c000
	v_add_u32_e32 v142, s35, v178
	v_add_u32_e32 v168, s57, v178
	ds_read_b128 v[128:131], v142
	ds_read_b128 v[132:135], v142 offset:1024
	ds_read_b128 v[136:139], v142 offset:2048
	ds_read_b128 v[142:145], v142 offset:3072
	ds_read_b128 v[146:149], v168
	ds_read_b128 v[150:153], v168 offset:1024
	ds_read_b128 v[154:157], v168 offset:2048
	ds_read_b128 v[168:171], v168 offset:3072
	s_add_u32 s10, s10, s48
	s_addc_u32 s11, s11, 0
	s_mov_b32 m0, s27
	v_lshl_add_u64 v[214:215], s[10:11], 0, v[162:163]
	ds_read_b128 v[172:175], v179 offset:32768
	ds_read_b128 v[180:183], v179 offset:33792
	ds_read_b128 v[184:187], v179 offset:34816
	ds_read_b128 v[188:191], v179 offset:35840
	ds_read_b128 v[192:195], v179 offset:36864
	ds_read_b128 v[200:203], v179 offset:37888
	ds_read_b128 v[206:209], v179 offset:38912
	ds_read_b128 v[210:213], v179 offset:39936
	global_load_lds_dwordx4 v[214:215], off
	v_lshl_add_u64 v[214:215], s[10:11], 0, v[160:161]
	s_mov_b32 m0, s15
	s_nop 0
	global_load_lds_dwordx4 v[214:215], off
	s_waitcnt vmcnt(8)
	s_waitcnt lgkmcnt(0)
	s_barrier
	s_setprio 1
	s_waitcnt lgkmcnt(0)
	v_mfma_f32_16x16x32_bf16 v[124:127], v[128:131], v[172:175], v[124:127]
	v_mfma_f32_16x16x32_bf16 v[120:123], v[136:139], v[172:175], v[120:123]
	v_mfma_f32_16x16x32_bf16 v[108:111], v[128:131], v[184:187], v[108:111]
	v_mfma_f32_16x16x32_bf16 v[104:107], v[136:139], v[184:187], v[104:107]
	v_mfma_f32_16x16x32_bf16 v[92:95], v[128:131], v[192:195], v[92:95]
	v_mfma_f32_16x16x32_bf16 v[88:91], v[136:139], v[192:195], v[88:91]
	v_mfma_f32_16x16x32_bf16 v[76:79], v[128:131], v[206:209], v[76:79]
	v_mfma_f32_16x16x32_bf16 v[72:75], v[136:139], v[206:209], v[72:75]
	v_mfma_f32_16x16x32_bf16 v[124:127], v[132:135], v[180:183], v[124:127]
	v_mfma_f32_16x16x32_bf16 v[120:123], v[142:145], v[180:183], v[120:123]
	v_mfma_f32_16x16x32_bf16 v[108:111], v[132:135], v[188:191], v[108:111]
	v_mfma_f32_16x16x32_bf16 v[104:107], v[142:145], v[188:191], v[104:107]
	v_mfma_f32_16x16x32_bf16 v[92:95], v[132:135], v[200:203], v[92:95]
	v_mfma_f32_16x16x32_bf16 v[88:91], v[142:145], v[200:203], v[88:91]
	v_mfma_f32_16x16x32_bf16 v[76:79], v[132:135], v[210:213], v[76:79]
	v_mfma_f32_16x16x32_bf16 v[72:75], v[142:145], v[210:213], v[72:75]
	s_setprio 0
	s_setprio 1
	v_mfma_f32_16x16x32_bf16 v[116:119], v[146:149], v[172:175], v[116:119]
	v_mfma_f32_16x16x32_bf16 v[112:115], v[154:157], v[172:175], v[112:115]
	v_mfma_f32_16x16x32_bf16 v[100:103], v[146:149], v[184:187], v[100:103]
	v_mfma_f32_16x16x32_bf16 v[96:99], v[154:157], v[184:187], v[96:99]
	v_mfma_f32_16x16x32_bf16 v[84:87], v[146:149], v[192:195], v[84:87]
	v_mfma_f32_16x16x32_bf16 v[80:83], v[154:157], v[192:195], v[80:83]
	v_mfma_f32_16x16x32_bf16 v[68:71], v[146:149], v[206:209], v[68:71]
	v_mfma_f32_16x16x32_bf16 v[64:67], v[154:157], v[206:209], v[64:67]
	v_mfma_f32_16x16x32_bf16 v[116:119], v[150:153], v[180:183], v[116:119]
	v_mfma_f32_16x16x32_bf16 v[112:115], v[168:171], v[180:183], v[112:115]
	v_mfma_f32_16x16x32_bf16 v[100:103], v[150:153], v[188:191], v[100:103]
	v_mfma_f32_16x16x32_bf16 v[96:99], v[168:171], v[188:191], v[96:99]
	v_mfma_f32_16x16x32_bf16 v[84:87], v[150:153], v[200:203], v[84:87]
	v_mfma_f32_16x16x32_bf16 v[80:83], v[168:171], v[200:203], v[80:83]
	v_mfma_f32_16x16x32_bf16 v[68:71], v[150:153], v[210:213], v[68:71]
	v_mfma_f32_16x16x32_bf16 v[64:67], v[168:171], v[210:213], v[64:67]
	s_setprio 0
	s_barrier
	s_add_i32 s10, s35, s74
	v_lshl_add_u64 v[176:177], v[176:177], 0, s[36:37]
	s_mov_b32 m0, s10
	ds_read_b128 v[172:175], v179 offset:49152
	ds_read_b128 v[180:183], v179 offset:50176
	ds_read_b128 v[184:187], v179 offset:51200
	ds_read_b128 v[188:191], v179 offset:52224
	ds_read_b128 v[192:195], v179 offset:53248
	ds_read_b128 v[200:203], v179 offset:54272
	ds_read_b128 v[206:209], v179 offset:55296
	ds_read_b128 v[210:213], v179 offset:56320
	global_load_lds_dwordx4 v[176:177], off
	v_lshl_add_u64 v[176:177], v[196:197], 0, s[36:37]
	s_add_i32 m0, s10, 0x2000
	s_add_i32 s10, s57, s74
	global_load_lds_dwordx4 v[176:177], off
	v_lshl_add_u64 v[176:177], v[198:199], 0, s[36:37]
	s_mov_b32 m0, s10
	s_nop 0
	global_load_lds_dwordx4 v[176:177], off
	v_lshl_add_u64 v[176:177], v[204:205], 0, s[36:37]
	s_add_i32 m0, s10, 0x2000
	s_nop 0
	global_load_lds_dwordx4 v[176:177], off
	v_lshl_add_u64 v[176:177], s[8:9], 0, v[162:163]
	s_mov_b32 m0, s28
	s_nop 0
	global_load_lds_dwordx4 v[176:177], off
	v_lshl_add_u64 v[176:177], s[8:9], 0, v[160:161]
	s_mov_b32 m0, s29
	s_nop 0
	global_load_lds_dwordx4 v[176:177], off
	s_waitcnt vmcnt(8)
	s_waitcnt lgkmcnt(0)
	s_barrier
	s_setprio 1
	s_waitcnt lgkmcnt(0)
	v_mfma_f32_16x16x32_bf16 v[60:63], v[128:131], v[172:175], v[60:63]
	v_mfma_f32_16x16x32_bf16 v[56:59], v[136:139], v[172:175], v[56:59]
	v_mfma_f32_16x16x32_bf16 v[44:47], v[128:131], v[184:187], v[44:47]
	v_mfma_f32_16x16x32_bf16 v[40:43], v[136:139], v[184:187], v[40:43]
	v_mfma_f32_16x16x32_bf16 v[28:31], v[128:131], v[192:195], v[28:31]
	v_mfma_f32_16x16x32_bf16 v[24:27], v[136:139], v[192:195], v[24:27]
	v_mfma_f32_16x16x32_bf16 v[12:15], v[128:131], v[206:209], v[12:15]
	v_mfma_f32_16x16x32_bf16 v[8:11], v[136:139], v[206:209], v[8:11]
	v_mfma_f32_16x16x32_bf16 v[60:63], v[132:135], v[180:183], v[60:63]
	v_mfma_f32_16x16x32_bf16 v[56:59], v[142:145], v[180:183], v[56:59]
	v_mfma_f32_16x16x32_bf16 v[44:47], v[132:135], v[188:191], v[44:47]
	v_mfma_f32_16x16x32_bf16 v[40:43], v[142:145], v[188:191], v[40:43]
	v_mfma_f32_16x16x32_bf16 v[28:31], v[132:135], v[200:203], v[28:31]
	v_mfma_f32_16x16x32_bf16 v[24:27], v[142:145], v[200:203], v[24:27]
	v_mfma_f32_16x16x32_bf16 v[12:15], v[132:135], v[210:213], v[12:15]
	v_mfma_f32_16x16x32_bf16 v[8:11], v[142:145], v[210:213], v[8:11]
	s_setprio 0
	s_setprio 1
	v_mfma_f32_16x16x32_bf16 v[52:55], v[146:149], v[172:175], v[52:55]
	v_mfma_f32_16x16x32_bf16 v[48:51], v[154:157], v[172:175], v[48:51]
	v_mfma_f32_16x16x32_bf16 v[36:39], v[146:149], v[184:187], v[36:39]
	v_mfma_f32_16x16x32_bf16 v[32:35], v[154:157], v[184:187], v[32:35]
	v_mfma_f32_16x16x32_bf16 v[20:23], v[146:149], v[192:195], v[20:23]
	v_mfma_f32_16x16x32_bf16 v[16:19], v[154:157], v[192:195], v[16:19]
	v_mfma_f32_16x16x32_bf16 v[4:7], v[146:149], v[206:209], v[4:7]
	v_mfma_f32_16x16x32_bf16 v[0:3], v[154:157], v[206:209], v[0:3]
	v_mfma_f32_16x16x32_bf16 v[52:55], v[150:153], v[180:183], v[52:55]
	v_mfma_f32_16x16x32_bf16 v[48:51], v[168:171], v[180:183], v[48:51]
	v_mfma_f32_16x16x32_bf16 v[36:39], v[150:153], v[188:191], v[36:39]
	v_mfma_f32_16x16x32_bf16 v[32:35], v[168:171], v[188:191], v[32:35]
	v_mfma_f32_16x16x32_bf16 v[20:23], v[150:153], v[200:203], v[20:23]
	v_mfma_f32_16x16x32_bf16 v[16:19], v[168:171], v[200:203], v[16:19]
	v_mfma_f32_16x16x32_bf16 v[4:7], v[150:153], v[210:213], v[4:7]
	v_mfma_f32_16x16x32_bf16 v[0:3], v[168:171], v[210:213], v[0:3]
	s_setprio 0
	s_add_u32 s24, s24, 0x100
	s_addc_u32 s38, s38, 0
	s_add_u32 s6, s6, 0x10000
	s_addc_u32 s7, s7, 0
	s_cmp_ge_u32 s56, s12
	s_mov_b32 s8, s56
	s_cbranch_scc0 .LBB0_333
	s_and_b64 vcc, exec, s[52:53]
	s_cbranch_vccz .LBB0_336
	s_barrier

.LBB0_374:
	s_add_u32 s6, s6, 0x80
	s_addc_u32 s7, s7, 0
	s_add_u32 s10, s8, 0x100
	v_mov_b32_e32 v0, 0
	s_addc_u32 s11, s9, 0
	s_mov_b32 s8, 0
	v_mov_b32_e32 v1, v0
	v_mov_b32_e32 v2, v0
	v_mov_b32_e32 v3, v0
	v_mov_b32_e32 v4, v0
	v_mov_b32_e32 v5, v0
	v_mov_b32_e32 v6, v0
	v_mov_b32_e32 v7, v0
	v_mov_b32_e32 v16, v0
	v_mov_b32_e32 v17, v0
	v_mov_b32_e32 v18, v0
	v_mov_b32_e32 v19, v0
	v_mov_b32_e32 v20, v0
	v_mov_b32_e32 v21, v0
	v_mov_b32_e32 v22, v0
	v_mov_b32_e32 v23, v0
	v_mov_b32_e32 v32, v0
	v_mov_b32_e32 v33, v0
	v_mov_b32_e32 v34, v0
	v_mov_b32_e32 v35, v0
	v_mov_b32_e32 v36, v0
	v_mov_b32_e32 v37, v0
	v_mov_b32_e32 v38, v0
	v_mov_b32_e32 v39, v0
	v_mov_b32_e32 v48, v0
	v_mov_b32_e32 v49, v0
	v_mov_b32_e32 v50, v0
	v_mov_b32_e32 v51, v0
	v_mov_b32_e32 v52, v0
	v_mov_b32_e32 v53, v0
	v_mov_b32_e32 v54, v0
	v_mov_b32_e32 v55, v0
	v_mov_b32_e32 v8, v0
	v_mov_b32_e32 v9, v0
	v_mov_b32_e32 v10, v0
	v_mov_b32_e32 v11, v0
	v_mov_b32_e32 v12, v0
	v_mov_b32_e32 v13, v0
	v_mov_b32_e32 v14, v0
	v_mov_b32_e32 v15, v0
	v_mov_b32_e32 v24, v0
	v_mov_b32_e32 v25, v0
	v_mov_b32_e32 v26, v0
	v_mov_b32_e32 v27, v0
	v_mov_b32_e32 v28, v0
	v_mov_b32_e32 v29, v0
	v_mov_b32_e32 v30, v0
	v_mov_b32_e32 v31, v0
	v_mov_b32_e32 v40, v0
	v_mov_b32_e32 v41, v0
	v_mov_b32_e32 v42, v0
	v_mov_b32_e32 v43, v0
	v_mov_b32_e32 v44, v0
	v_mov_b32_e32 v45, v0
	v_mov_b32_e32 v46, v0
	v_mov_b32_e32 v47, v0
	v_mov_b32_e32 v56, v0
	v_mov_b32_e32 v57, v0
	v_mov_b32_e32 v58, v0
	v_mov_b32_e32 v59, v0
	v_mov_b32_e32 v60, v0
	v_mov_b32_e32 v61, v0
	v_mov_b32_e32 v62, v0
	v_mov_b32_e32 v63, v0
	v_mov_b32_e32 v64, v0
	v_mov_b32_e32 v65, v0
	v_mov_b32_e32 v66, v0
	v_mov_b32_e32 v67, v0
	v_mov_b32_e32 v68, v0
	v_mov_b32_e32 v69, v0
	v_mov_b32_e32 v70, v0
	v_mov_b32_e32 v71, v0
	v_mov_b32_e32 v80, v0
	v_mov_b32_e32 v81, v0
	v_mov_b32_e32 v82, v0
	v_mov_b32_e32 v83, v0
	v_mov_b32_e32 v84, v0
	v_mov_b32_e32 v85, v0
	v_mov_b32_e32 v86, v0
	v_mov_b32_e32 v87, v0
	v_mov_b32_e32 v96, v0
	v_mov_b32_e32 v97, v0
	v_mov_b32_e32 v98, v0
	v_mov_b32_e32 v99, v0
	v_mov_b32_e32 v100, v0
	v_mov_b32_e32 v101, v0
	v_mov_b32_e32 v102, v0
	v_mov_b32_e32 v103, v0
	v_mov_b32_e32 v112, v0
	v_mov_b32_e32 v113, v0
	v_mov_b32_e32 v114, v0
	v_mov_b32_e32 v115, v0
	v_mov_b32_e32 v116, v0
	v_mov_b32_e32 v117, v0
	v_mov_b32_e32 v118, v0
	v_mov_b32_e32 v119, v0
	v_mov_b32_e32 v72, v0
	v_mov_b32_e32 v73, v0
	v_mov_b32_e32 v74, v0
	v_mov_b32_e32 v75, v0
	v_mov_b32_e32 v76, v0
	v_mov_b32_e32 v77, v0
	v_mov_b32_e32 v78, v0
	v_mov_b32_e32 v79, v0
	v_mov_b32_e32 v88, v0
	v_mov_b32_e32 v89, v0
	v_mov_b32_e32 v90, v0
	v_mov_b32_e32 v91, v0
	v_mov_b32_e32 v92, v0
	v_mov_b32_e32 v93, v0
	v_mov_b32_e32 v94, v0
	v_mov_b32_e32 v95, v0
	v_mov_b32_e32 v104, v0
	v_mov_b32_e32 v105, v0
	v_mov_b32_e32 v106, v0
	v_mov_b32_e32 v107, v0
	v_mov_b32_e32 v108, v0
	v_mov_b32_e32 v109, v0
	v_mov_b32_e32 v110, v0
	v_mov_b32_e32 v111, v0
	v_mov_b32_e32 v120, v0
	v_mov_b32_e32 v121, v0
	v_mov_b32_e32 v122, v0
	v_mov_b32_e32 v123, v0
	v_mov_b32_e32 v124, v0
	v_mov_b32_e32 v125, v0
	v_mov_b32_e32 v126, v0
	v_mov_b32_e32 v127, v0
	s_branch .Lrot_375

.Lrot_375:
	s_add_i32 s24, s8, 2
	s_add_u32 s35, s6, 0x80
	s_addc_u32 s9, s7, 0
	s_add_i32 s38, 0, 0x10000
	s_cmp_eq_u32 s94, s8
	s_cselect_b32 s9, s43, s9
	s_cselect_b32 s8, s42, s35
	s_cselect_b32 s57, s55, s11
	s_cselect_b32 s56, s54, s10
	s_add_i32 s35, 0, 0x14000
	v_add_u32_e32 v142, s38, v178
	v_add_u32_e32 v168, s35, v178
	ds_read_b128 v[128:131], v142
	ds_read_b128 v[132:135], v142 offset:1024
	ds_read_b128 v[136:139], v142 offset:2048
	ds_read_b128 v[142:145], v142 offset:3072
	ds_read_b128 v[146:149], v168
	ds_read_b128 v[150:153], v168 offset:1024
	ds_read_b128 v[154:157], v168 offset:2048
	ds_read_b128 v[168:171], v168 offset:3072
	v_lshl_add_u64 v[176:177], s[6:7], 0, v[164:165]
	s_add_i32 m0, s15, 0xc000
	ds_read_b128 v[172:175], v179
	ds_read_b128 v[180:183], v179 offset:1024
	ds_read_b128 v[184:187], v179 offset:2048
	ds_read_b128 v[188:191], v179 offset:3072
	ds_read_b128 v[192:195], v179 offset:4096
	ds_read_b128 v[200:203], v179 offset:5120
	ds_read_b128 v[206:209], v179 offset:6144
	ds_read_b128 v[210:213], v179 offset:7168
	global_load_lds_dwordx4 v[176:177], off
	v_lshl_add_u64 v[176:177], s[6:7], 0, v[166:167]
	s_add_i32 m0, s15, 0xe000
	s_nop 0
	global_load_lds_dwordx4 v[176:177], off
	s_waitcnt vmcnt(8)
	s_waitcnt lgkmcnt(0)
	s_barrier
	s_setprio 1
	s_waitcnt lgkmcnt(0)
	v_mfma_f32_16x16x32_bf16 v[124:127], v[128:131], v[172:175], v[124:127]
	v_mfma_f32_16x16x32_bf16 v[120:123], v[136:139], v[172:175], v[120:123]
	v_mfma_f32_16x16x32_bf16 v[108:111], v[128:131], v[184:187], v[108:111]
	v_mfma_f32_16x16x32_bf16 v[104:107], v[136:139], v[184:187], v[104:107]
	v_mfma_f32_16x16x32_bf16 v[92:95], v[128:131], v[192:195], v[92:95]
	v_mfma_f32_16x16x32_bf16 v[88:91], v[136:139], v[192:195], v[88:91]
	v_mfma_f32_16x16x32_bf16 v[76:79], v[128:131], v[206:209], v[76:79]
	v_mfma_f32_16x16x32_bf16 v[72:75], v[136:139], v[206:209], v[72:75]
	v_mfma_f32_16x16x32_bf16 v[124:127], v[132:135], v[180:183], v[124:127]
	v_mfma_f32_16x16x32_bf16 v[120:123], v[142:145], v[180:183], v[120:123]
	v_mfma_f32_16x16x32_bf16 v[108:111], v[132:135], v[188:191], v[108:111]
	v_mfma_f32_16x16x32_bf16 v[104:107], v[142:145], v[188:191], v[104:107]
	v_mfma_f32_16x16x32_bf16 v[92:95], v[132:135], v[200:203], v[92:95]
	v_mfma_f32_16x16x32_bf16 v[88:91], v[142:145], v[200:203], v[88:91]
	v_mfma_f32_16x16x32_bf16 v[76:79], v[132:135], v[210:213], v[76:79]
	v_mfma_f32_16x16x32_bf16 v[72:75], v[142:145], v[210:213], v[72:75]
	s_setprio 0
	s_setprio 1
	v_mfma_f32_16x16x32_bf16 v[116:119], v[146:149], v[172:175], v[116:119]
	v_mfma_f32_16x16x32_bf16 v[112:115], v[154:157], v[172:175], v[112:115]
	v_mfma_f32_16x16x32_bf16 v[100:103], v[146:149], v[184:187], v[100:103]
	v_mfma_f32_16x16x32_bf16 v[96:99], v[154:157], v[184:187], v[96:99]
	v_mfma_f32_16x16x32_bf16 v[84:87], v[146:149], v[192:195], v[84:87]
	v_mfma_f32_16x16x32_bf16 v[80:83], v[154:157], v[192:195], v[80:83]
	v_mfma_f32_16x16x32_bf16 v[68:71], v[146:149], v[206:209], v[68:71]
	v_mfma_f32_16x16x32_bf16 v[64:67], v[154:157], v[206:209], v[64:67]
	v_mfma_f32_16x16x32_bf16 v[116:119], v[150:153], v[180:183], v[116:119]
	v_mfma_f32_16x16x32_bf16 v[112:115], v[168:171], v[180:183], v[112:115]
	v_mfma_f32_16x16x32_bf16 v[100:103], v[150:153], v[188:191], v[100:103]
	v_mfma_f32_16x16x32_bf16 v[96:99], v[168:171], v[188:191], v[96:99]
	v_mfma_f32_16x16x32_bf16 v[84:87], v[150:153], v[200:203], v[84:87]
	v_mfma_f32_16x16x32_bf16 v[80:83], v[168:171], v[200:203], v[80:83]
	v_mfma_f32_16x16x32_bf16 v[68:71], v[150:153], v[210:213], v[68:71]
	v_mfma_f32_16x16x32_bf16 v[64:67], v[168:171], v[210:213], v[64:67]
	s_setprio 0
	s_barrier
	s_add_i32 s38, s38, s75
	v_lshl_add_u64 v[176:177], s[56:57], 0, v[140:141]
	s_mov_b32 m0, s38
	ds_read_b128 v[172:175], v179 offset:16384
	ds_read_b128 v[180:183], v179 offset:17408
	ds_read_b128 v[184:187], v179 offset:18432
	ds_read_b128 v[188:191], v179 offset:19456
	ds_read_b128 v[192:195], v179 offset:20480
	ds_read_b128 v[200:203], v179 offset:21504
	ds_read_b128 v[206:209], v179 offset:22528
	ds_read_b128 v[210:213], v179 offset:23552
	global_load_lds_dwordx4 v[176:177], off
	s_add_i32 m0, s38, 0x2000
	v_lshl_add_u64 v[196:197], s[56:57], 0, v[158:159]
	s_add_u32 s56, s56, s13
	s_addc_u32 s57, s57, 0
	s_add_i32 s35, s35, s75
	global_load_lds_dwordx4 v[196:197], off
	v_lshl_add_u64 v[198:199], s[56:57], 0, v[140:141]
	s_mov_b32 m0, s35
	v_lshl_add_u64 v[204:205], s[56:57], 0, v[158:159]
	global_load_lds_dwordx4 v[198:199], off
	s_add_i32 m0, s35, 0x2000
	v_lshl_add_u64 v[214:215], s[8:9], 0, v[162:163]
	global_load_lds_dwordx4 v[204:205], off
	s_mov_b32 m0, s15
	v_lshl_add_u64 v[216:217], s[8:9], 0, v[160:161]
	global_load_lds_dwordx4 v[214:215], off
	s_mov_b32 m0, s26
	s_nop 0
	global_load_lds_dwordx4 v[216:217], off
	s_waitcnt vmcnt(8)
	s_waitcnt lgkmcnt(0)
	s_barrier
	s_setprio 1
	s_waitcnt lgkmcnt(0)
	v_mfma_f32_16x16x32_bf16 v[60:63], v[128:131], v[172:175], v[60:63]
	v_mfma_f32_16x16x32_bf16 v[56:59], v[136:139], v[172:175], v[56:59]
	v_mfma_f32_16x16x32_bf16 v[44:47], v[128:131], v[184:187], v[44:47]
	v_mfma_f32_16x16x32_bf16 v[40:43], v[136:139], v[184:187], v[40:43]
	v_mfma_f32_16x16x32_bf16 v[28:31], v[128:131], v[192:195], v[28:31]
	v_mfma_f32_16x16x32_bf16 v[24:27], v[136:139], v[192:195], v[24:27]
	v_mfma_f32_16x16x32_bf16 v[12:15], v[128:131], v[206:209], v[12:15]
	v_mfma_f32_16x16x32_bf16 v[8:11], v[136:139], v[206:209], v[8:11]
	v_mfma_f32_16x16x32_bf16 v[60:63], v[132:135], v[180:183], v[60:63]
	v_mfma_f32_16x16x32_bf16 v[56:59], v[142:145], v[180:183], v[56:59]
	v_mfma_f32_16x16x32_bf16 v[44:47], v[132:135], v[188:191], v[44:47]
	v_mfma_f32_16x16x32_bf16 v[40:43], v[142:145], v[188:191], v[40:43]
	v_mfma_f32_16x16x32_bf16 v[28:31], v[132:135], v[200:203], v[28:31]
	v_mfma_f32_16x16x32_bf16 v[24:27], v[142:145], v[200:203], v[24:27]
	v_mfma_f32_16x16x32_bf16 v[12:15], v[132:135], v[210:213], v[12:15]
	v_mfma_f32_16x16x32_bf16 v[8:11], v[142:145], v[210:213], v[8:11]
	s_setprio 0
	s_setprio 1
	v_mfma_f32_16x16x32_bf16 v[52:55], v[146:149], v[172:175], v[52:55]
	v_mfma_f32_16x16x32_bf16 v[48:51], v[154:157], v[172:175], v[48:51]
	v_mfma_f32_16x16x32_bf16 v[36:39], v[146:149], v[184:187], v[36:39]
	v_mfma_f32_16x16x32_bf16 v[32:35], v[154:157], v[184:187], v[32:35]
	v_mfma_f32_16x16x32_bf16 v[20:23], v[146:149], v[192:195], v[20:23]
	v_mfma_f32_16x16x32_bf16 v[16:19], v[154:157], v[192:195], v[16:19]
	v_mfma_f32_16x16x32_bf16 v[4:7], v[146:149], v[206:209], v[4:7]
	v_mfma_f32_16x16x32_bf16 v[0:3], v[154:157], v[206:209], v[0:3]
	v_mfma_f32_16x16x32_bf16 v[52:55], v[150:153], v[180:183], v[52:55]
	v_mfma_f32_16x16x32_bf16 v[48:51], v[168:171], v[180:183], v[48:51]
	v_mfma_f32_16x16x32_bf16 v[36:39], v[150:153], v[188:191], v[36:39]
	v_mfma_f32_16x16x32_bf16 v[32:35], v[168:171], v[188:191], v[32:35]
	v_mfma_f32_16x16x32_bf16 v[20:23], v[150:153], v[200:203], v[20:23]
	v_mfma_f32_16x16x32_bf16 v[16:19], v[168:171], v[200:203], v[16:19]
	v_mfma_f32_16x16x32_bf16 v[4:7], v[150:153], v[210:213], v[4:7]
	v_mfma_f32_16x16x32_bf16 v[0:3], v[168:171], v[210:213], v[0:3]
	s_setprio 0
	s_barrier
	s_add_i32 s35, 0, 0x18000
	s_add_i32 s38, 0, 0x1c000
	v_add_u32_e32 v142, s35, v178
	v_add_u32_e32 v168, s38, v178
	ds_read_b128 v[128:131], v142
	ds_read_b128 v[132:135], v142 offset:1024
	ds_read_b128 v[136:139], v142 offset:2048
	ds_read_b128 v[142:145], v142 offset:3072
	ds_read_b128 v[146:149], v168
	ds_read_b128 v[150:153], v168 offset:1024
	ds_read_b128 v[154:157], v168 offset:2048
	ds_read_b128 v[168:171], v168 offset:3072
	s_add_u32 s8, s8, s48
	s_addc_u32 s9, s9, 0
	s_mov_b32 m0, s27
	v_lshl_add_u64 v[218:219], s[8:9], 0, v[162:163]
	ds_read_b128 v[172:175], v179 offset:32768
	ds_read_b128 v[180:183], v179 offset:33792
	ds_read_b128 v[184:187], v179 offset:34816
	ds_read_b128 v[188:191], v179 offset:35840
	ds_read_b128 v[192:195], v179 offset:36864
	ds_read_b128 v[200:203], v179 offset:37888
	ds_read_b128 v[206:209], v179 offset:38912
	ds_read_b128 v[210:213], v179 offset:39936
	global_load_lds_dwordx4 v[218:219], off
	v_lshl_add_u64 v[218:219], s[8:9], 0, v[160:161]
	s_mov_b32 m0, s28
	s_nop 0
	global_load_lds_dwordx4 v[218:219], off
	s_waitcnt vmcnt(8)
	s_waitcnt lgkmcnt(0)
	s_barrier
	s_setprio 1
	s_waitcnt lgkmcnt(0)
	v_mfma_f32_16x16x32_bf16 v[124:127], v[128:131], v[172:175], v[124:127]
	v_mfma_f32_16x16x32_bf16 v[120:123], v[136:139], v[172:175], v[120:123]
	v_mfma_f32_16x16x32_bf16 v[108:111], v[128:131], v[184:187], v[108:111]
	v_mfma_f32_16x16x32_bf16 v[104:107], v[136:139], v[184:187], v[104:107]
	v_mfma_f32_16x16x32_bf16 v[92:95], v[128:131], v[192:195], v[92:95]
	v_mfma_f32_16x16x32_bf16 v[88:91], v[136:139], v[192:195], v[88:91]
	v_mfma_f32_16x16x32_bf16 v[76:79], v[128:131], v[206:209], v[76:79]
	v_mfma_f32_16x16x32_bf16 v[72:75], v[136:139], v[206:209], v[72:75]
	v_mfma_f32_16x16x32_bf16 v[124:127], v[132:135], v[180:183], v[124:127]
	v_mfma_f32_16x16x32_bf16 v[120:123], v[142:145], v[180:183], v[120:123]
	v_mfma_f32_16x16x32_bf16 v[108:111], v[132:135], v[188:191], v[108:111]
	v_mfma_f32_16x16x32_bf16 v[104:107], v[142:145], v[188:191], v[104:107]
	v_mfma_f32_16x16x32_bf16 v[92:95], v[132:135], v[200:203], v[92:95]
	v_mfma_f32_16x16x32_bf16 v[88:91], v[142:145], v[200:203], v[88:91]
	v_mfma_f32_16x16x32_bf16 v[76:79], v[132:135], v[210:213], v[76:79]
	v_mfma_f32_16x16x32_bf16 v[72:75], v[142:145], v[210:213], v[72:75]
	s_setprio 0
	s_setprio 1
	v_mfma_f32_16x16x32_bf16 v[116:119], v[146:149], v[172:175], v[116:119]
	v_mfma_f32_16x16x32_bf16 v[112:115], v[154:157], v[172:175], v[112:115]
	v_mfma_f32_16x16x32_bf16 v[100:103], v[146:149], v[184:187], v[100:103]
	v_mfma_f32_16x16x32_bf16 v[96:99], v[154:157], v[184:187], v[96:99]
	v_mfma_f32_16x16x32_bf16 v[84:87], v[146:149], v[192:195], v[84:87]
	v_mfma_f32_16x16x32_bf16 v[80:83], v[154:157], v[192:195], v[80:83]
	v_mfma_f32_16x16x32_bf16 v[68:71], v[146:149], v[206:209], v[68:71]
	v_mfma_f32_16x16x32_bf16 v[64:67], v[154:157], v[206:209], v[64:67]
	v_mfma_f32_16x16x32_bf16 v[116:119], v[150:153], v[180:183], v[116:119]
	v_mfma_f32_16x16x32_bf16 v[112:115], v[168:171], v[180:183], v[112:115]
	v_mfma_f32_16x16x32_bf16 v[100:103], v[150:153], v[188:191], v[100:103]
	v_mfma_f32_16x16x32_bf16 v[96:99], v[168:171], v[188:191], v[96:99]
	v_mfma_f32_16x16x32_bf16 v[84:87], v[150:153], v[200:203], v[84:87]
	v_mfma_f32_16x16x32_bf16 v[80:83], v[168:171], v[200:203], v[80:83]
	v_mfma_f32_16x16x32_bf16 v[68:71], v[150:153], v[210:213], v[68:71]
	v_mfma_f32_16x16x32_bf16 v[64:67], v[168:171], v[210:213], v[64:67]
	s_setprio 0
	s_barrier
	s_add_i32 s8, s35, s75
	v_lshl_add_u64 v[176:177], v[176:177], 0, s[36:37]
	s_mov_b32 m0, s8
	ds_read_b128 v[172:175], v179 offset:49152
	ds_read_b128 v[180:183], v179 offset:50176
	ds_read_b128 v[184:187], v179 offset:51200
	ds_read_b128 v[188:191], v179 offset:52224
	ds_read_b128 v[192:195], v179 offset:53248
	ds_read_b128 v[200:203], v179 offset:54272
	ds_read_b128 v[206:209], v179 offset:55296
	ds_read_b128 v[210:213], v179 offset:56320
	global_load_lds_dwordx4 v[176:177], off
	v_lshl_add_u64 v[176:177], v[196:197], 0, s[36:37]
	s_add_i32 m0, s8, 0x2000
	s_add_i32 s8, s38, s75
	global_load_lds_dwordx4 v[176:177], off
	v_lshl_add_u64 v[176:177], v[198:199], 0, s[36:37]
	s_mov_b32 m0, s8
	s_nop 0
	global_load_lds_dwordx4 v[176:177], off
	v_lshl_add_u64 v[176:177], v[204:205], 0, s[36:37]
	s_add_i32 m0, s8, 0x2000
	s_nop 0
	global_load_lds_dwordx4 v[176:177], off
	v_lshl_add_u64 v[176:177], v[214:215], 0, s[36:37]
	s_mov_b32 m0, s29
	s_nop 0
	global_load_lds_dwordx4 v[176:177], off
	v_lshl_add_u64 v[176:177], v[216:217], 0, s[36:37]
	s_mov_b32 m0, s58
	s_nop 0
	global_load_lds_dwordx4 v[176:177], off
	s_waitcnt vmcnt(8)
	s_waitcnt lgkmcnt(0)
	s_barrier
	s_setprio 1
	s_waitcnt lgkmcnt(0)
	v_mfma_f32_16x16x32_bf16 v[60:63], v[128:131], v[172:175], v[60:63]
	v_mfma_f32_16x16x32_bf16 v[56:59], v[136:139], v[172:175], v[56:59]
	v_mfma_f32_16x16x32_bf16 v[44:47], v[128:131], v[184:187], v[44:47]
	v_mfma_f32_16x16x32_bf16 v[40:43], v[136:139], v[184:187], v[40:43]
	v_mfma_f32_16x16x32_bf16 v[28:31], v[128:131], v[192:195], v[28:31]
	v_mfma_f32_16x16x32_bf16 v[24:27], v[136:139], v[192:195], v[24:27]
	v_mfma_f32_16x16x32_bf16 v[12:15], v[128:131], v[206:209], v[12:15]
	v_mfma_f32_16x16x32_bf16 v[8:11], v[136:139], v[206:209], v[8:11]
	v_mfma_f32_16x16x32_bf16 v[60:63], v[132:135], v[180:183], v[60:63]
	v_mfma_f32_16x16x32_bf16 v[56:59], v[142:145], v[180:183], v[56:59]
	v_mfma_f32_16x16x32_bf16 v[44:47], v[132:135], v[188:191], v[44:47]
	v_mfma_f32_16x16x32_bf16 v[40:43], v[142:145], v[188:191], v[40:43]
	v_mfma_f32_16x16x32_bf16 v[28:31], v[132:135], v[200:203], v[28:31]
	v_mfma_f32_16x16x32_bf16 v[24:27], v[142:145], v[200:203], v[24:27]
	v_mfma_f32_16x16x32_bf16 v[12:15], v[132:135], v[210:213], v[12:15]
	v_mfma_f32_16x16x32_bf16 v[8:11], v[142:145], v[210:213], v[8:11]
	s_setprio 0
	s_setprio 1
	v_mfma_f32_16x16x32_bf16 v[52:55], v[146:149], v[172:175], v[52:55]
	v_mfma_f32_16x16x32_bf16 v[48:51], v[154:157], v[172:175], v[48:51]
	v_mfma_f32_16x16x32_bf16 v[36:39], v[146:149], v[184:187], v[36:39]
	v_mfma_f32_16x16x32_bf16 v[32:35], v[154:157], v[184:187], v[32:35]
	v_mfma_f32_16x16x32_bf16 v[20:23], v[146:149], v[192:195], v[20:23]
	v_mfma_f32_16x16x32_bf16 v[16:19], v[154:157], v[192:195], v[16:19]
	v_mfma_f32_16x16x32_bf16 v[4:7], v[146:149], v[206:209], v[4:7]
	v_mfma_f32_16x16x32_bf16 v[0:3], v[154:157], v[206:209], v[0:3]
	v_mfma_f32_16x16x32_bf16 v[52:55], v[150:153], v[180:183], v[52:55]
	v_mfma_f32_16x16x32_bf16 v[48:51], v[168:171], v[180:183], v[48:51]
	v_mfma_f32_16x16x32_bf16 v[36:39], v[150:153], v[188:191], v[36:39]
	v_mfma_f32_16x16x32_bf16 v[32:35], v[168:171], v[188:191], v[32:35]
	v_mfma_f32_16x16x32_bf16 v[20:23], v[150:153], v[200:203], v[20:23]
	v_mfma_f32_16x16x32_bf16 v[16:19], v[168:171], v[200:203], v[16:19]
	v_mfma_f32_16x16x32_bf16 v[4:7], v[150:153], v[210:213], v[4:7]
	v_mfma_f32_16x16x32_bf16 v[0:3], v[168:171], v[210:213], v[0:3]
	s_setprio 0
	s_add_u32 s6, s6, 0x100
	s_addc_u32 s7, s7, 0
	s_add_u32 s10, s10, 0x100
	s_addc_u32 s11, s11, 0
	s_cmp_ge_u32 s24, s12
	s_mov_b32 s8, s24
	s_cbranch_scc0 .LBB0_375
	s_and_b64 vcc, exec, s[52:53]
	s_cbranch_vccz .LBB0_378
	s_barrier

.LBB0_551:
	s_ashr_i32 s51, s50, 31
	s_lshl_b64 s[4:5], s[50:51], 19
	s_add_u32 s52, s68, s4
	s_addc_u32 s53, s69, s5
	s_and_b64 s[4:5], s[40:41], exec
	s_cselect_b32 s4, s53, s7
	s_cselect_b32 s5, s52, s6
	s_ashr_i32 s47, s46, 31
	s_lshl_b64 s[10:11], s[46:47], 19
	s_add_u32 s54, s13, s10
	s_addc_u32 s55, s15, s11
	s_and_b64 s[10:11], s[40:41], exec
	s_cselect_b32 s24, s55, s9
	s_cselect_b32 s38, s54, s8
	s_add_u32 s6, s6, 0x40080
	s_addc_u32 s7, s7, 0
	s_add_u32 s47, s8, 0x100
	v_mov_b32_e32 v0, 0
	s_addc_u32 s51, s9, 0
	s_mov_b32 s56, -2
	v_mov_b32_e32 v1, v0
	v_mov_b32_e32 v2, v0
	v_mov_b32_e32 v3, v0
	v_mov_b32_e32 v4, v0
	v_mov_b32_e32 v5, v0
	v_mov_b32_e32 v6, v0
	v_mov_b32_e32 v7, v0
	v_mov_b32_e32 v16, v0
	v_mov_b32_e32 v17, v0
	v_mov_b32_e32 v18, v0
	v_mov_b32_e32 v19, v0
	v_mov_b32_e32 v20, v0
	v_mov_b32_e32 v21, v0
	v_mov_b32_e32 v22, v0
	v_mov_b32_e32 v23, v0
	v_mov_b32_e32 v32, v0
	v_mov_b32_e32 v33, v0
	v_mov_b32_e32 v34, v0
	v_mov_b32_e32 v35, v0
	v_mov_b32_e32 v36, v0
	v_mov_b32_e32 v37, v0
	v_mov_b32_e32 v38, v0
	v_mov_b32_e32 v39, v0
	v_mov_b32_e32 v48, v0
	v_mov_b32_e32 v49, v0
	v_mov_b32_e32 v50, v0
	v_mov_b32_e32 v51, v0
	v_mov_b32_e32 v52, v0
	v_mov_b32_e32 v53, v0
	v_mov_b32_e32 v54, v0
	v_mov_b32_e32 v55, v0
	v_mov_b32_e32 v8, v0
	v_mov_b32_e32 v9, v0
	v_mov_b32_e32 v10, v0
	v_mov_b32_e32 v11, v0
	v_mov_b32_e32 v12, v0
	v_mov_b32_e32 v13, v0
	v_mov_b32_e32 v14, v0
	v_mov_b32_e32 v15, v0
	v_mov_b32_e32 v24, v0
	v_mov_b32_e32 v25, v0
	v_mov_b32_e32 v26, v0
	v_mov_b32_e32 v27, v0
	v_mov_b32_e32 v28, v0
	v_mov_b32_e32 v29, v0
	v_mov_b32_e32 v30, v0
	v_mov_b32_e32 v31, v0
	v_mov_b32_e32 v40, v0
	v_mov_b32_e32 v41, v0
	v_mov_b32_e32 v42, v0
	v_mov_b32_e32 v43, v0
	v_mov_b32_e32 v44, v0
	v_mov_b32_e32 v45, v0
	v_mov_b32_e32 v46, v0
	v_mov_b32_e32 v47, v0
	v_mov_b32_e32 v56, v0
	v_mov_b32_e32 v57, v0
	v_mov_b32_e32 v58, v0
	v_mov_b32_e32 v59, v0
	v_mov_b32_e32 v60, v0
	v_mov_b32_e32 v61, v0
	v_mov_b32_e32 v62, v0
	v_mov_b32_e32 v63, v0
	v_mov_b32_e32 v64, v0
	v_mov_b32_e32 v65, v0
	v_mov_b32_e32 v66, v0
	v_mov_b32_e32 v67, v0
	v_mov_b32_e32 v68, v0
	v_mov_b32_e32 v69, v0
	v_mov_b32_e32 v70, v0
	v_mov_b32_e32 v71, v0
	v_mov_b32_e32 v80, v0
	v_mov_b32_e32 v81, v0
	v_mov_b32_e32 v82, v0
	v_mov_b32_e32 v83, v0
	v_mov_b32_e32 v84, v0
	v_mov_b32_e32 v85, v0
	v_mov_b32_e32 v86, v0
	v_mov_b32_e32 v87, v0
	v_mov_b32_e32 v96, v0
	v_mov_b32_e32 v97, v0
	v_mov_b32_e32 v98, v0
	v_mov_b32_e32 v99, v0
	v_mov_b32_e32 v100, v0
	v_mov_b32_e32 v101, v0
	v_mov_b32_e32 v102, v0
	v_mov_b32_e32 v103, v0
	v_mov_b32_e32 v112, v0
	v_mov_b32_e32 v113, v0
	v_mov_b32_e32 v114, v0
	v_mov_b32_e32 v115, v0
	v_mov_b32_e32 v116, v0
	v_mov_b32_e32 v117, v0
	v_mov_b32_e32 v118, v0
	v_mov_b32_e32 v119, v0
	v_mov_b32_e32 v72, v0
	v_mov_b32_e32 v73, v0
	v_mov_b32_e32 v74, v0
	v_mov_b32_e32 v75, v0
	v_mov_b32_e32 v76, v0
	v_mov_b32_e32 v77, v0
	v_mov_b32_e32 v78, v0
	v_mov_b32_e32 v79, v0
	v_mov_b32_e32 v88, v0
	v_mov_b32_e32 v89, v0
	v_mov_b32_e32 v90, v0
	v_mov_b32_e32 v91, v0
	v_mov_b32_e32 v92, v0
	v_mov_b32_e32 v93, v0
	v_mov_b32_e32 v94, v0
	v_mov_b32_e32 v95, v0
	v_mov_b32_e32 v104, v0
	v_mov_b32_e32 v105, v0
	v_mov_b32_e32 v106, v0
	v_mov_b32_e32 v107, v0
	v_mov_b32_e32 v108, v0
	v_mov_b32_e32 v109, v0
	v_mov_b32_e32 v110, v0
	v_mov_b32_e32 v111, v0
	v_mov_b32_e32 v120, v0
	v_mov_b32_e32 v121, v0
	v_mov_b32_e32 v122, v0
	v_mov_b32_e32 v123, v0
	v_mov_b32_e32 v124, v0
	v_mov_b32_e32 v125, v0
	v_mov_b32_e32 v126, v0
	v_mov_b32_e32 v127, v0
	s_branch .Lrot_552

.Lrot_552:
	s_add_u32 s8, s6, 0xfffc0080
	s_addc_u32 s9, s7, -1
	s_add_i32 s35, 0, 0x10000
	s_cmp_eq_u32 s56, 12
	s_cselect_b32 s11, s4, s9
	s_cselect_b32 s10, s5, s8
	v_add_u32_e32 v140, s35, v165
	s_cselect_b32 s9, s24, s51
	s_cselect_b32 s8, s38, s47
	s_add_i32 s57, 0, 0x14000
	ds_read_b128 v[158:161], v140
	ds_read_b128 v[168:171], v140 offset:1024
	ds_read_b128 v[172:175], v140 offset:2048
	ds_read_b128 v[176:179], v140 offset:3072
	v_add_u32_e32 v140, s57, v165
	ds_read_b128 v[180:183], v140
	ds_read_b128 v[184:187], v140 offset:1024
	ds_read_b128 v[206:209], v140 offset:2048
	ds_read_b128 v[210:213], v140 offset:3072
	v_lshl_add_u64 v[142:143], s[6:7], 0, v[136:137]
	s_add_i32 m0, s66, 0xc000
	ds_read_b128 v[214:217], v166
	ds_read_b128 v[218:221], v166 offset:1024
	ds_read_b128 v[222:225], v166 offset:2048
	ds_read_b128 v[226:229], v166 offset:3072
	ds_read_b128 v[230:233], v166 offset:4096
	ds_read_b128 v[234:237], v166 offset:5120
	ds_read_b128 v[238:241], v166 offset:6144
	ds_read_b128 v[242:245], v166 offset:7168
	global_load_lds_dwordx4 v[142:143], off
	v_lshl_add_u64 v[142:143], s[6:7], 0, v[138:139]
	s_add_i32 m0, s66, 0xe000
	s_nop 0
	global_load_lds_dwordx4 v[142:143], off
	s_waitcnt vmcnt(8)
	s_waitcnt lgkmcnt(0)
	s_barrier
	s_setprio 1
	s_waitcnt lgkmcnt(0)
	v_mfma_f32_16x16x32_bf16 v[124:127], v[158:161], v[214:217], v[124:127]
	v_mfma_f32_16x16x32_bf16 v[120:123], v[172:175], v[214:217], v[120:123]
	v_mfma_f32_16x16x32_bf16 v[108:111], v[158:161], v[222:225], v[108:111]
	v_mfma_f32_16x16x32_bf16 v[104:107], v[172:175], v[222:225], v[104:107]
	v_mfma_f32_16x16x32_bf16 v[92:95], v[158:161], v[230:233], v[92:95]
	v_mfma_f32_16x16x32_bf16 v[88:91], v[172:175], v[230:233], v[88:91]
	v_mfma_f32_16x16x32_bf16 v[76:79], v[158:161], v[238:241], v[76:79]
	v_mfma_f32_16x16x32_bf16 v[72:75], v[172:175], v[238:241], v[72:75]
	v_mfma_f32_16x16x32_bf16 v[124:127], v[168:171], v[218:221], v[124:127]
	v_mfma_f32_16x16x32_bf16 v[120:123], v[176:179], v[218:221], v[120:123]
	v_mfma_f32_16x16x32_bf16 v[108:111], v[168:171], v[226:229], v[108:111]
	v_mfma_f32_16x16x32_bf16 v[104:107], v[176:179], v[226:229], v[104:107]
	v_mfma_f32_16x16x32_bf16 v[92:95], v[168:171], v[234:237], v[92:95]
	v_mfma_f32_16x16x32_bf16 v[88:91], v[176:179], v[234:237], v[88:91]
	v_mfma_f32_16x16x32_bf16 v[76:79], v[168:171], v[242:245], v[76:79]
	v_mfma_f32_16x16x32_bf16 v[72:75], v[176:179], v[242:245], v[72:75]
	s_setprio 0
	s_setprio 1
	v_mfma_f32_16x16x32_bf16 v[116:119], v[180:183], v[214:217], v[116:119]
	v_mfma_f32_16x16x32_bf16 v[112:115], v[206:209], v[214:217], v[112:115]
	v_mfma_f32_16x16x32_bf16 v[100:103], v[180:183], v[222:225], v[100:103]
	v_mfma_f32_16x16x32_bf16 v[96:99], v[206:209], v[222:225], v[96:99]
	v_mfma_f32_16x16x32_bf16 v[84:87], v[180:183], v[230:233], v[84:87]
	v_mfma_f32_16x16x32_bf16 v[80:83], v[206:209], v[230:233], v[80:83]
	v_mfma_f32_16x16x32_bf16 v[68:71], v[180:183], v[238:241], v[68:71]
	v_mfma_f32_16x16x32_bf16 v[64:67], v[206:209], v[238:241], v[64:67]
	v_mfma_f32_16x16x32_bf16 v[116:119], v[184:187], v[218:221], v[116:119]
	v_mfma_f32_16x16x32_bf16 v[112:115], v[210:213], v[218:221], v[112:115]
	v_mfma_f32_16x16x32_bf16 v[100:103], v[184:187], v[226:229], v[100:103]
	v_mfma_f32_16x16x32_bf16 v[96:99], v[210:213], v[226:229], v[96:99]
	v_mfma_f32_16x16x32_bf16 v[84:87], v[184:187], v[234:237], v[84:87]
	v_mfma_f32_16x16x32_bf16 v[80:83], v[210:213], v[234:237], v[80:83]
	v_mfma_f32_16x16x32_bf16 v[68:71], v[184:187], v[242:245], v[68:71]
	v_mfma_f32_16x16x32_bf16 v[64:67], v[210:213], v[242:245], v[64:67]
	s_setprio 0
	s_barrier
	s_add_i32 s35, s35, s12
	v_lshl_add_u64 v[142:143], s[8:9], 0, v[132:133]
	s_mov_b32 m0, s35
	ds_read_b128 v[214:217], v166 offset:16384
	ds_read_b128 v[218:221], v166 offset:17408
	ds_read_b128 v[222:225], v166 offset:18432
	ds_read_b128 v[226:229], v166 offset:19456
	ds_read_b128 v[230:233], v166 offset:20480
	ds_read_b128 v[234:237], v166 offset:21504
	ds_read_b128 v[238:241], v166 offset:22528
	ds_read_b128 v[242:245], v166 offset:23552
	global_load_lds_dwordx4 v[142:143], off
	s_add_i32 m0, s35, 0x2000
	s_add_u32 s58, s8, 0x40000
	v_lshl_add_u64 v[144:145], s[8:9], 0, v[128:129]
	s_addc_u32 s59, s9, 0
	s_add_i32 s35, s57, s12
	global_load_lds_dwordx4 v[144:145], off
	v_lshl_add_u64 v[146:147], s[58:59], 0, v[132:133]
	s_mov_b32 m0, s35
	v_lshl_add_u64 v[148:149], s[10:11], 0, v[130:131]
	global_load_lds_dwordx4 v[146:147], off
	v_lshl_add_u64 v[146:147], s[58:59], 0, v[128:129]
	s_add_i32 m0, s35, 0x2000
	s_nop 0
	global_load_lds_dwordx4 v[146:147], off
	v_lshl_add_u64 v[146:147], s[10:11], 0, v[134:135]
	s_mov_b32 m0, s66
	s_nop 0
	global_load_lds_dwordx4 v[146:147], off
	s_mov_b32 m0, s67
	s_nop 0
	global_load_lds_dwordx4 v[148:149], off
	s_waitcnt vmcnt(8)
	s_waitcnt lgkmcnt(0)
	s_barrier
	s_setprio 1
	s_waitcnt lgkmcnt(0)
	v_mfma_f32_16x16x32_bf16 v[60:63], v[158:161], v[214:217], v[60:63]
	v_mfma_f32_16x16x32_bf16 v[56:59], v[172:175], v[214:217], v[56:59]
	v_mfma_f32_16x16x32_bf16 v[44:47], v[158:161], v[222:225], v[44:47]
	v_mfma_f32_16x16x32_bf16 v[40:43], v[172:175], v[222:225], v[40:43]
	v_mfma_f32_16x16x32_bf16 v[28:31], v[158:161], v[230:233], v[28:31]
	v_mfma_f32_16x16x32_bf16 v[24:27], v[172:175], v[230:233], v[24:27]
	v_mfma_f32_16x16x32_bf16 v[12:15], v[158:161], v[238:241], v[12:15]
	v_mfma_f32_16x16x32_bf16 v[8:11], v[172:175], v[238:241], v[8:11]
	v_mfma_f32_16x16x32_bf16 v[60:63], v[168:171], v[218:221], v[60:63]
	v_mfma_f32_16x16x32_bf16 v[56:59], v[176:179], v[218:221], v[56:59]
	v_mfma_f32_16x16x32_bf16 v[44:47], v[168:171], v[226:229], v[44:47]
	v_mfma_f32_16x16x32_bf16 v[40:43], v[176:179], v[226:229], v[40:43]
	v_mfma_f32_16x16x32_bf16 v[28:31], v[168:171], v[234:237], v[28:31]
	v_mfma_f32_16x16x32_bf16 v[24:27], v[176:179], v[234:237], v[24:27]
	v_mfma_f32_16x16x32_bf16 v[12:15], v[168:171], v[242:245], v[12:15]
	v_mfma_f32_16x16x32_bf16 v[8:11], v[176:179], v[242:245], v[8:11]
	s_setprio 0
	s_setprio 1
	v_mfma_f32_16x16x32_bf16 v[52:55], v[180:183], v[214:217], v[52:55]
	v_mfma_f32_16x16x32_bf16 v[48:51], v[206:209], v[214:217], v[48:51]
	v_mfma_f32_16x16x32_bf16 v[36:39], v[180:183], v[222:225], v[36:39]
	v_mfma_f32_16x16x32_bf16 v[32:35], v[206:209], v[222:225], v[32:35]
	v_mfma_f32_16x16x32_bf16 v[20:23], v[180:183], v[230:233], v[20:23]
	v_mfma_f32_16x16x32_bf16 v[16:19], v[206:209], v[230:233], v[16:19]
	v_mfma_f32_16x16x32_bf16 v[4:7], v[180:183], v[238:241], v[4:7]
	v_mfma_f32_16x16x32_bf16 v[0:3], v[206:209], v[238:241], v[0:3]
	v_mfma_f32_16x16x32_bf16 v[52:55], v[184:187], v[218:221], v[52:55]
	v_mfma_f32_16x16x32_bf16 v[48:51], v[210:213], v[218:221], v[48:51]
	v_mfma_f32_16x16x32_bf16 v[36:39], v[184:187], v[226:229], v[36:39]
	v_mfma_f32_16x16x32_bf16 v[32:35], v[210:213], v[226:229], v[32:35]
	v_mfma_f32_16x16x32_bf16 v[20:23], v[184:187], v[234:237], v[20:23]
	v_mfma_f32_16x16x32_bf16 v[16:19], v[210:213], v[234:237], v[16:19]
	v_mfma_f32_16x16x32_bf16 v[4:7], v[184:187], v[242:245], v[4:7]
	v_mfma_f32_16x16x32_bf16 v[0:3], v[210:213], v[242:245], v[0:3]
	s_setprio 0
	s_barrier
	s_add_i32 s35, 0, 0x18000
	v_add_u32_e32 v140, s35, v165
	s_add_i32 s57, 0, 0x1c000
	ds_read_b128 v[158:161], v140
	ds_read_b128 v[168:171], v140 offset:1024
	ds_read_b128 v[172:175], v140 offset:2048
	ds_read_b128 v[176:179], v140 offset:3072
	v_add_u32_e32 v140, s57, v165
	ds_read_b128 v[180:183], v140
	ds_read_b128 v[184:187], v140 offset:1024
	ds_read_b128 v[206:209], v140 offset:2048
	ds_read_b128 v[210:213], v140 offset:3072
	s_add_u32 s10, s10, 0x40000
	s_addc_u32 s11, s11, 0
	s_mov_b32 m0, s74
	v_lshl_add_u64 v[150:151], s[10:11], 0, v[134:135]
	ds_read_b128 v[214:217], v166 offset:32768
	ds_read_b128 v[218:221], v166 offset:33792
	ds_read_b128 v[222:225], v166 offset:34816
	ds_read_b128 v[226:229], v166 offset:35840
	ds_read_b128 v[230:233], v166 offset:36864
	ds_read_b128 v[234:237], v166 offset:37888
	ds_read_b128 v[238:241], v166 offset:38912
	ds_read_b128 v[242:245], v166 offset:39936
	global_load_lds_dwordx4 v[150:151], off
	v_lshl_add_u64 v[150:151], s[10:11], 0, v[130:131]
	s_mov_b32 m0, s75
	s_nop 0
	global_load_lds_dwordx4 v[150:151], off
	s_waitcnt vmcnt(8)
	s_waitcnt lgkmcnt(0)
	s_barrier
	s_setprio 1
	s_waitcnt lgkmcnt(0)
	v_mfma_f32_16x16x32_bf16 v[124:127], v[158:161], v[214:217], v[124:127]
	v_mfma_f32_16x16x32_bf16 v[120:123], v[172:175], v[214:217], v[120:123]
	v_mfma_f32_16x16x32_bf16 v[108:111], v[158:161], v[222:225], v[108:111]
	v_mfma_f32_16x16x32_bf16 v[104:107], v[172:175], v[222:225], v[104:107]
	v_mfma_f32_16x16x32_bf16 v[92:95], v[158:161], v[230:233], v[92:95]
	v_mfma_f32_16x16x32_bf16 v[88:91], v[172:175], v[230:233], v[88:91]
	v_mfma_f32_16x16x32_bf16 v[76:79], v[158:161], v[238:241], v[76:79]
	v_mfma_f32_16x16x32_bf16 v[72:75], v[172:175], v[238:241], v[72:75]
	v_mfma_f32_16x16x32_bf16 v[124:127], v[168:171], v[218:221], v[124:127]
	v_mfma_f32_16x16x32_bf16 v[120:123], v[176:179], v[218:221], v[120:123]
	v_mfma_f32_16x16x32_bf16 v[108:111], v[168:171], v[226:229], v[108:111]
	v_mfma_f32_16x16x32_bf16 v[104:107], v[176:179], v[226:229], v[104:107]
	v_mfma_f32_16x16x32_bf16 v[92:95], v[168:171], v[234:237], v[92:95]
	v_mfma_f32_16x16x32_bf16 v[88:91], v[176:179], v[234:237], v[88:91]
	v_mfma_f32_16x16x32_bf16 v[76:79], v[168:171], v[242:245], v[76:79]
	v_mfma_f32_16x16x32_bf16 v[72:75], v[176:179], v[242:245], v[72:75]
	s_setprio 0
	s_setprio 1
	v_mfma_f32_16x16x32_bf16 v[116:119], v[180:183], v[214:217], v[116:119]
	v_mfma_f32_16x16x32_bf16 v[112:115], v[206:209], v[214:217], v[112:115]
	v_mfma_f32_16x16x32_bf16 v[100:103], v[180:183], v[222:225], v[100:103]
	v_mfma_f32_16x16x32_bf16 v[96:99], v[206:209], v[222:225], v[96:99]
	v_mfma_f32_16x16x32_bf16 v[84:87], v[180:183], v[230:233], v[84:87]
	v_mfma_f32_16x16x32_bf16 v[80:83], v[206:209], v[230:233], v[80:83]
	v_mfma_f32_16x16x32_bf16 v[68:71], v[180:183], v[238:241], v[68:71]
	v_mfma_f32_16x16x32_bf16 v[64:67], v[206:209], v[238:241], v[64:67]
	v_mfma_f32_16x16x32_bf16 v[116:119], v[184:187], v[218:221], v[116:119]
	v_mfma_f32_16x16x32_bf16 v[112:115], v[210:213], v[218:221], v[112:115]
	v_mfma_f32_16x16x32_bf16 v[100:103], v[184:187], v[226:229], v[100:103]
	v_mfma_f32_16x16x32_bf16 v[96:99], v[210:213], v[226:229], v[96:99]
	v_mfma_f32_16x16x32_bf16 v[84:87], v[184:187], v[234:237], v[84:87]
	v_mfma_f32_16x16x32_bf16 v[80:83], v[210:213], v[234:237], v[80:83]
	v_mfma_f32_16x16x32_bf16 v[68:71], v[184:187], v[242:245], v[68:71]
	v_mfma_f32_16x16x32_bf16 v[64:67], v[210:213], v[242:245], v[64:67]
	s_setprio 0
	s_barrier
	s_add_i32 s10, s35, s12
	v_lshl_add_u64 v[142:143], v[142:143], 0, s[36:37]
	s_mov_b32 m0, s10
	ds_read_b128 v[214:217], v166 offset:49152
	ds_read_b128 v[218:221], v166 offset:50176
	ds_read_b128 v[222:225], v166 offset:51200
	ds_read_b128 v[226:229], v166 offset:52224
	ds_read_b128 v[230:233], v166 offset:53248
	ds_read_b128 v[234:237], v166 offset:54272
	ds_read_b128 v[238:241], v166 offset:55296
	ds_read_b128 v[242:245], v166 offset:56320
	global_load_lds_dwordx4 v[142:143], off
	s_add_i32 m0, s10, 0x2000
	s_add_u32 s8, s8, 0x40080
	v_lshl_add_u64 v[142:143], v[144:145], 0, s[36:37]
	s_addc_u32 s9, s9, 0
	s_add_i32 s10, s57, s12
	global_load_lds_dwordx4 v[142:143], off
	v_lshl_add_u64 v[142:143], s[8:9], 0, v[132:133]
	s_mov_b32 m0, s10
	s_nop 0
	global_load_lds_dwordx4 v[142:143], off
	v_lshl_add_u64 v[142:143], s[8:9], 0, v[128:129]
	s_add_i32 m0, s10, 0x2000
	s_nop 0
	global_load_lds_dwordx4 v[142:143], off
	v_lshl_add_u64 v[142:143], v[146:147], 0, s[36:37]
	s_mov_b32 m0, s26
	s_nop 0
	global_load_lds_dwordx4 v[142:143], off
	v_lshl_add_u64 v[142:143], v[148:149], 0, s[36:37]
	s_mov_b32 m0, s27
	s_nop 0
	global_load_lds_dwordx4 v[142:143], off
	s_waitcnt vmcnt(8)
	s_waitcnt lgkmcnt(0)
	s_barrier
	s_setprio 1
	s_waitcnt lgkmcnt(0)
	v_mfma_f32_16x16x32_bf16 v[60:63], v[158:161], v[214:217], v[60:63]
	v_mfma_f32_16x16x32_bf16 v[56:59], v[172:175], v[214:217], v[56:59]
	v_mfma_f32_16x16x32_bf16 v[44:47], v[158:161], v[222:225], v[44:47]
	v_mfma_f32_16x16x32_bf16 v[40:43], v[172:175], v[222:225], v[40:43]
	v_mfma_f32_16x16x32_bf16 v[28:31], v[158:161], v[230:233], v[28:31]
	v_mfma_f32_16x16x32_bf16 v[24:27], v[172:175], v[230:233], v[24:27]
	v_mfma_f32_16x16x32_bf16 v[12:15], v[158:161], v[238:241], v[12:15]
	v_mfma_f32_16x16x32_bf16 v[8:11], v[172:175], v[238:241], v[8:11]
	v_mfma_f32_16x16x32_bf16 v[60:63], v[168:171], v[218:221], v[60:63]
	v_mfma_f32_16x16x32_bf16 v[56:59], v[176:179], v[218:221], v[56:59]
	v_mfma_f32_16x16x32_bf16 v[44:47], v[168:171], v[226:229], v[44:47]
	v_mfma_f32_16x16x32_bf16 v[40:43], v[176:179], v[226:229], v[40:43]
	v_mfma_f32_16x16x32_bf16 v[28:31], v[168:171], v[234:237], v[28:31]
	v_mfma_f32_16x16x32_bf16 v[24:27], v[176:179], v[234:237], v[24:27]
	v_mfma_f32_16x16x32_bf16 v[12:15], v[168:171], v[242:245], v[12:15]
	v_mfma_f32_16x16x32_bf16 v[8:11], v[176:179], v[242:245], v[8:11]
	s_setprio 0
	s_setprio 1
	v_mfma_f32_16x16x32_bf16 v[52:55], v[180:183], v[214:217], v[52:55]
	v_mfma_f32_16x16x32_bf16 v[48:51], v[206:209], v[214:217], v[48:51]
	v_mfma_f32_16x16x32_bf16 v[36:39], v[180:183], v[222:225], v[36:39]
	v_mfma_f32_16x16x32_bf16 v[32:35], v[206:209], v[222:225], v[32:35]
	v_mfma_f32_16x16x32_bf16 v[20:23], v[180:183], v[230:233], v[20:23]
	v_mfma_f32_16x16x32_bf16 v[16:19], v[206:209], v[230:233], v[16:19]
	v_mfma_f32_16x16x32_bf16 v[4:7], v[180:183], v[238:241], v[4:7]
	v_mfma_f32_16x16x32_bf16 v[0:3], v[206:209], v[238:241], v[0:3]
	v_mfma_f32_16x16x32_bf16 v[52:55], v[184:187], v[218:221], v[52:55]
	v_mfma_f32_16x16x32_bf16 v[48:51], v[210:213], v[218:221], v[48:51]
	v_mfma_f32_16x16x32_bf16 v[36:39], v[184:187], v[226:229], v[36:39]
	v_mfma_f32_16x16x32_bf16 v[32:35], v[210:213], v[226:229], v[32:35]
	v_mfma_f32_16x16x32_bf16 v[20:23], v[184:187], v[234:237], v[20:23]
	v_mfma_f32_16x16x32_bf16 v[16:19], v[210:213], v[234:237], v[16:19]
	v_mfma_f32_16x16x32_bf16 v[4:7], v[184:187], v[242:245], v[4:7]
	v_mfma_f32_16x16x32_bf16 v[0:3], v[210:213], v[242:245], v[0:3]
	s_setprio 0
	s_add_i32 s56, s56, 2
	s_add_u32 s6, s6, 0x100
	s_addc_u32 s7, s7, 0
	s_add_u32 s47, s47, 0x100
	s_addc_u32 s51, s51, 0
	s_cmp_gt_u32 s56, 13
	s_cbranch_scc0 .LBB0_552
	s_and_b64 vcc, exec, s[44:45]
	s_cbranch_vccz .LBB0_555
	s_barrier

.LBB0_713:
	s_ashr_i32 s51, s50, 31
	s_lshl_b64 s[10:11], s[50:51], 19
	s_add_u32 s52, s15, s10
	s_addc_u32 s53, s16, s11
	s_and_b64 s[10:11], s[40:41], exec
	s_cselect_b32 s24, s53, s7
	s_cselect_b32 s51, s52, s6
	s_ashr_i32 s49, s48, 31
	s_lshl_b64 s[10:11], s[48:49], 19
	s_add_u32 s54, s12, s10
	s_addc_u32 s55, s13, s11
	s_and_b64 s[10:11], s[40:41], exec
	s_cselect_b32 s49, s55, s9
	s_cselect_b32 s56, s54, s8
	s_add_u32 s6, s6, 0x40080
	s_addc_u32 s7, s7, 0
	s_add_u32 s57, s8, 0x100
	v_mov_b32_e32 v0, 0
	s_addc_u32 s58, s9, 0
	s_mov_b32 s59, -2
	v_mov_b32_e32 v1, v0
	v_mov_b32_e32 v2, v0
	v_mov_b32_e32 v3, v0
	v_mov_b32_e32 v4, v0
	v_mov_b32_e32 v5, v0
	v_mov_b32_e32 v6, v0
	v_mov_b32_e32 v7, v0
	v_mov_b32_e32 v16, v0
	v_mov_b32_e32 v17, v0
	v_mov_b32_e32 v18, v0
	v_mov_b32_e32 v19, v0
	v_mov_b32_e32 v20, v0
	v_mov_b32_e32 v21, v0
	v_mov_b32_e32 v22, v0
	v_mov_b32_e32 v23, v0
	v_mov_b32_e32 v32, v0
	v_mov_b32_e32 v33, v0
	v_mov_b32_e32 v34, v0
	v_mov_b32_e32 v35, v0
	v_mov_b32_e32 v36, v0
	v_mov_b32_e32 v37, v0
	v_mov_b32_e32 v38, v0
	v_mov_b32_e32 v39, v0
	v_mov_b32_e32 v48, v0
	v_mov_b32_e32 v49, v0
	v_mov_b32_e32 v50, v0
	v_mov_b32_e32 v51, v0
	v_mov_b32_e32 v52, v0
	v_mov_b32_e32 v53, v0
	v_mov_b32_e32 v54, v0
	v_mov_b32_e32 v55, v0
	v_mov_b32_e32 v8, v0
	v_mov_b32_e32 v9, v0
	v_mov_b32_e32 v10, v0
	v_mov_b32_e32 v11, v0
	v_mov_b32_e32 v12, v0
	v_mov_b32_e32 v13, v0
	v_mov_b32_e32 v14, v0
	v_mov_b32_e32 v15, v0
	v_mov_b32_e32 v24, v0
	v_mov_b32_e32 v25, v0
	v_mov_b32_e32 v26, v0
	v_mov_b32_e32 v27, v0
	v_mov_b32_e32 v28, v0
	v_mov_b32_e32 v29, v0
	v_mov_b32_e32 v30, v0
	v_mov_b32_e32 v31, v0
	v_mov_b32_e32 v40, v0
	v_mov_b32_e32 v41, v0
	v_mov_b32_e32 v42, v0
	v_mov_b32_e32 v43, v0
	v_mov_b32_e32 v44, v0
	v_mov_b32_e32 v45, v0
	v_mov_b32_e32 v46, v0
	v_mov_b32_e32 v47, v0
	v_mov_b32_e32 v56, v0
	v_mov_b32_e32 v57, v0
	v_mov_b32_e32 v58, v0
	v_mov_b32_e32 v59, v0
	v_mov_b32_e32 v60, v0
	v_mov_b32_e32 v61, v0
	v_mov_b32_e32 v62, v0
	v_mov_b32_e32 v63, v0
	v_mov_b32_e32 v64, v0
	v_mov_b32_e32 v65, v0
	v_mov_b32_e32 v66, v0
	v_mov_b32_e32 v67, v0
	v_mov_b32_e32 v68, v0
	v_mov_b32_e32 v69, v0
	v_mov_b32_e32 v70, v0
	v_mov_b32_e32 v71, v0
	v_mov_b32_e32 v80, v0
	v_mov_b32_e32 v81, v0
	v_mov_b32_e32 v82, v0
	v_mov_b32_e32 v83, v0
	v_mov_b32_e32 v84, v0
	v_mov_b32_e32 v85, v0
	v_mov_b32_e32 v86, v0
	v_mov_b32_e32 v87, v0
	v_mov_b32_e32 v96, v0
	v_mov_b32_e32 v97, v0
	v_mov_b32_e32 v98, v0
	v_mov_b32_e32 v99, v0
	v_mov_b32_e32 v100, v0
	v_mov_b32_e32 v101, v0
	v_mov_b32_e32 v102, v0
	v_mov_b32_e32 v103, v0
	v_mov_b32_e32 v112, v0
	v_mov_b32_e32 v113, v0
	v_mov_b32_e32 v114, v0
	v_mov_b32_e32 v115, v0
	v_mov_b32_e32 v116, v0
	v_mov_b32_e32 v117, v0
	v_mov_b32_e32 v118, v0
	v_mov_b32_e32 v119, v0
	v_mov_b32_e32 v72, v0
	v_mov_b32_e32 v73, v0
	v_mov_b32_e32 v74, v0
	v_mov_b32_e32 v75, v0
	v_mov_b32_e32 v76, v0
	v_mov_b32_e32 v77, v0
	v_mov_b32_e32 v78, v0
	v_mov_b32_e32 v79, v0
	v_mov_b32_e32 v88, v0
	v_mov_b32_e32 v89, v0
	v_mov_b32_e32 v90, v0
	v_mov_b32_e32 v91, v0
	v_mov_b32_e32 v92, v0
	v_mov_b32_e32 v93, v0
	v_mov_b32_e32 v94, v0
	v_mov_b32_e32 v95, v0
	v_mov_b32_e32 v104, v0
	v_mov_b32_e32 v105, v0
	v_mov_b32_e32 v106, v0
	v_mov_b32_e32 v107, v0
	v_mov_b32_e32 v108, v0
	v_mov_b32_e32 v109, v0
	v_mov_b32_e32 v110, v0
	v_mov_b32_e32 v111, v0
	v_mov_b32_e32 v120, v0
	v_mov_b32_e32 v121, v0
	v_mov_b32_e32 v122, v0
	v_mov_b32_e32 v123, v0
	v_mov_b32_e32 v124, v0
	v_mov_b32_e32 v125, v0
	v_mov_b32_e32 v126, v0
	v_mov_b32_e32 v127, v0
	s_branch .Lrot_714

.Lrot_714:
	s_add_u32 s8, s6, 0xfffc0080
	s_addc_u32 s9, s7, -1
	s_add_i32 s35, 0, 0x10000
	s_cmp_eq_u32 s59, 12
	s_cselect_b32 s11, s24, s9
	s_cselect_b32 s10, s51, s8
	v_add_u32_e32 v138, s35, v164
	s_cselect_b32 s9, s49, s58
	s_cselect_b32 s8, s56, s57
	s_add_i32 s66, 0, 0x14000
	ds_read_b128 v[158:161], v138
	ds_read_b128 v[166:169], v138 offset:1024
	ds_read_b128 v[170:173], v138 offset:2048
	ds_read_b128 v[174:177], v138 offset:3072
	v_add_u32_e32 v138, s66, v164
	ds_read_b128 v[178:181], v138
	ds_read_b128 v[182:185], v138 offset:1024
	ds_read_b128 v[206:209], v138 offset:2048
	ds_read_b128 v[210:213], v138 offset:3072
	v_lshl_add_u64 v[138:139], s[6:7], 0, v[134:135]
	s_add_i32 m0, s17, 0xc000
	ds_read_b128 v[214:217], v165
	ds_read_b128 v[218:221], v165 offset:1024
	ds_read_b128 v[222:225], v165 offset:2048
	ds_read_b128 v[226:229], v165 offset:3072
	ds_read_b128 v[230:233], v165 offset:4096
	ds_read_b128 v[234:237], v165 offset:5120
	ds_read_b128 v[238:241], v165 offset:6144
	ds_read_b128 v[242:245], v165 offset:7168
	global_load_lds_dwordx4 v[138:139], off
	v_lshl_add_u64 v[138:139], s[6:7], 0, v[136:137]
	s_add_i32 m0, s17, 0xe000
	s_nop 0
	global_load_lds_dwordx4 v[138:139], off
	s_waitcnt vmcnt(8)
	s_waitcnt lgkmcnt(0)
	s_barrier
	s_setprio 1
	s_waitcnt lgkmcnt(0)
	v_mfma_f32_16x16x32_bf16 v[124:127], v[158:161], v[214:217], v[124:127]
	v_mfma_f32_16x16x32_bf16 v[120:123], v[170:173], v[214:217], v[120:123]
	v_mfma_f32_16x16x32_bf16 v[108:111], v[158:161], v[222:225], v[108:111]
	v_mfma_f32_16x16x32_bf16 v[104:107], v[170:173], v[222:225], v[104:107]
	v_mfma_f32_16x16x32_bf16 v[92:95], v[158:161], v[230:233], v[92:95]
	v_mfma_f32_16x16x32_bf16 v[88:91], v[170:173], v[230:233], v[88:91]
	v_mfma_f32_16x16x32_bf16 v[76:79], v[158:161], v[238:241], v[76:79]
	v_mfma_f32_16x16x32_bf16 v[72:75], v[170:173], v[238:241], v[72:75]
	v_mfma_f32_16x16x32_bf16 v[124:127], v[166:169], v[218:221], v[124:127]
	v_mfma_f32_16x16x32_bf16 v[120:123], v[174:177], v[218:221], v[120:123]
	v_mfma_f32_16x16x32_bf16 v[108:111], v[166:169], v[226:229], v[108:111]
	v_mfma_f32_16x16x32_bf16 v[104:107], v[174:177], v[226:229], v[104:107]
	v_mfma_f32_16x16x32_bf16 v[92:95], v[166:169], v[234:237], v[92:95]
	v_mfma_f32_16x16x32_bf16 v[88:91], v[174:177], v[234:237], v[88:91]
	v_mfma_f32_16x16x32_bf16 v[76:79], v[166:169], v[242:245], v[76:79]
	v_mfma_f32_16x16x32_bf16 v[72:75], v[174:177], v[242:245], v[72:75]
	s_setprio 0
	s_setprio 1
	v_mfma_f32_16x16x32_bf16 v[116:119], v[178:181], v[214:217], v[116:119]
	v_mfma_f32_16x16x32_bf16 v[112:115], v[206:209], v[214:217], v[112:115]
	v_mfma_f32_16x16x32_bf16 v[100:103], v[178:181], v[222:225], v[100:103]
	v_mfma_f32_16x16x32_bf16 v[96:99], v[206:209], v[222:225], v[96:99]
	v_mfma_f32_16x16x32_bf16 v[84:87], v[178:181], v[230:233], v[84:87]
	v_mfma_f32_16x16x32_bf16 v[80:83], v[206:209], v[230:233], v[80:83]
	v_mfma_f32_16x16x32_bf16 v[68:71], v[178:181], v[238:241], v[68:71]
	v_mfma_f32_16x16x32_bf16 v[64:67], v[206:209], v[238:241], v[64:67]
	v_mfma_f32_16x16x32_bf16 v[116:119], v[182:185], v[218:221], v[116:119]
	v_mfma_f32_16x16x32_bf16 v[112:115], v[210:213], v[218:221], v[112:115]
	v_mfma_f32_16x16x32_bf16 v[100:103], v[182:185], v[226:229], v[100:103]
	v_mfma_f32_16x16x32_bf16 v[96:99], v[210:213], v[226:229], v[96:99]
	v_mfma_f32_16x16x32_bf16 v[84:87], v[182:185], v[234:237], v[84:87]
	v_mfma_f32_16x16x32_bf16 v[80:83], v[210:213], v[234:237], v[80:83]
	v_mfma_f32_16x16x32_bf16 v[68:71], v[182:185], v[242:245], v[68:71]
	v_mfma_f32_16x16x32_bf16 v[64:67], v[210:213], v[242:245], v[64:67]
	s_setprio 0
	s_barrier
	s_add_i32 s35, s35, s14
	v_lshl_add_u64 v[138:139], s[8:9], 0, v[140:141]
	s_mov_b32 m0, s35
	ds_read_b128 v[214:217], v165 offset:16384
	ds_read_b128 v[218:221], v165 offset:17408
	ds_read_b128 v[222:225], v165 offset:18432
	ds_read_b128 v[226:229], v165 offset:19456
	ds_read_b128 v[230:233], v165 offset:20480
	ds_read_b128 v[234:237], v165 offset:21504
	ds_read_b128 v[238:241], v165 offset:22528
	ds_read_b128 v[242:245], v165 offset:23552
	global_load_lds_dwordx4 v[138:139], off
	s_add_i32 m0, s35, 0x2000
	s_add_u32 s60, s8, 0x40000
	v_lshl_add_u64 v[142:143], s[8:9], 0, v[128:129]
	s_addc_u32 s61, s9, 0
	s_add_i32 s35, s66, s14
	global_load_lds_dwordx4 v[142:143], off
	v_lshl_add_u64 v[144:145], s[60:61], 0, v[140:141]
	s_mov_b32 m0, s35
	v_lshl_add_u64 v[146:147], s[10:11], 0, v[130:131]
	global_load_lds_dwordx4 v[144:145], off
	v_lshl_add_u64 v[144:145], s[60:61], 0, v[128:129]
	s_add_i32 m0, s35, 0x2000
	s_nop 0
	global_load_lds_dwordx4 v[144:145], off
	v_lshl_add_u64 v[144:145], s[10:11], 0, v[132:133]
	s_mov_b32 m0, s17
	s_nop 0
	global_load_lds_dwordx4 v[144:145], off
	s_mov_b32 m0, s25
	s_nop 0
	global_load_lds_dwordx4 v[146:147], off
	s_waitcnt vmcnt(8)
	s_waitcnt lgkmcnt(0)
	s_barrier
	s_setprio 1
	s_waitcnt lgkmcnt(0)
	v_mfma_f32_16x16x32_bf16 v[60:63], v[158:161], v[214:217], v[60:63]
	v_mfma_f32_16x16x32_bf16 v[56:59], v[170:173], v[214:217], v[56:59]
	v_mfma_f32_16x16x32_bf16 v[44:47], v[158:161], v[222:225], v[44:47]
	v_mfma_f32_16x16x32_bf16 v[40:43], v[170:173], v[222:225], v[40:43]
	v_mfma_f32_16x16x32_bf16 v[28:31], v[158:161], v[230:233], v[28:31]
	v_mfma_f32_16x16x32_bf16 v[24:27], v[170:173], v[230:233], v[24:27]
	v_mfma_f32_16x16x32_bf16 v[12:15], v[158:161], v[238:241], v[12:15]
	v_mfma_f32_16x16x32_bf16 v[8:11], v[170:173], v[238:241], v[8:11]
	v_mfma_f32_16x16x32_bf16 v[60:63], v[166:169], v[218:221], v[60:63]
	v_mfma_f32_16x16x32_bf16 v[56:59], v[174:177], v[218:221], v[56:59]
	v_mfma_f32_16x16x32_bf16 v[44:47], v[166:169], v[226:229], v[44:47]
	v_mfma_f32_16x16x32_bf16 v[40:43], v[174:177], v[226:229], v[40:43]
	v_mfma_f32_16x16x32_bf16 v[28:31], v[166:169], v[234:237], v[28:31]
	v_mfma_f32_16x16x32_bf16 v[24:27], v[174:177], v[234:237], v[24:27]
	v_mfma_f32_16x16x32_bf16 v[12:15], v[166:169], v[242:245], v[12:15]
	v_mfma_f32_16x16x32_bf16 v[8:11], v[174:177], v[242:245], v[8:11]
	s_setprio 0
	s_setprio 1
	v_mfma_f32_16x16x32_bf16 v[52:55], v[178:181], v[214:217], v[52:55]
	v_mfma_f32_16x16x32_bf16 v[48:51], v[206:209], v[214:217], v[48:51]
	v_mfma_f32_16x16x32_bf16 v[36:39], v[178:181], v[222:225], v[36:39]
	v_mfma_f32_16x16x32_bf16 v[32:35], v[206:209], v[222:225], v[32:35]
	v_mfma_f32_16x16x32_bf16 v[20:23], v[178:181], v[230:233], v[20:23]
	v_mfma_f32_16x16x32_bf16 v[16:19], v[206:209], v[230:233], v[16:19]
	v_mfma_f32_16x16x32_bf16 v[4:7], v[178:181], v[238:241], v[4:7]
	v_mfma_f32_16x16x32_bf16 v[0:3], v[206:209], v[238:241], v[0:3]
	v_mfma_f32_16x16x32_bf16 v[52:55], v[182:185], v[218:221], v[52:55]
	v_mfma_f32_16x16x32_bf16 v[48:51], v[210:213], v[218:221], v[48:51]
	v_mfma_f32_16x16x32_bf16 v[36:39], v[182:185], v[226:229], v[36:39]
	v_mfma_f32_16x16x32_bf16 v[32:35], v[210:213], v[226:229], v[32:35]
	v_mfma_f32_16x16x32_bf16 v[20:23], v[182:185], v[234:237], v[20:23]
	v_mfma_f32_16x16x32_bf16 v[16:19], v[210:213], v[234:237], v[16:19]
	v_mfma_f32_16x16x32_bf16 v[4:7], v[182:185], v[242:245], v[4:7]
	v_mfma_f32_16x16x32_bf16 v[0:3], v[210:213], v[242:245], v[0:3]
	s_setprio 0
	s_barrier
	s_add_i32 s35, 0, 0x18000
	v_add_u32_e32 v148, s35, v164
	s_add_i32 s60, 0, 0x1c000
	ds_read_b128 v[158:161], v148
	ds_read_b128 v[166:169], v148 offset:1024
	ds_read_b128 v[170:173], v148 offset:2048
	ds_read_b128 v[174:177], v148 offset:3072
	v_add_u32_e32 v148, s60, v164
	ds_read_b128 v[178:181], v148
	ds_read_b128 v[182:185], v148 offset:1024
	ds_read_b128 v[206:209], v148 offset:2048
	ds_read_b128 v[210:213], v148 offset:3072
	s_add_u32 s10, s10, 0x40000
	s_addc_u32 s11, s11, 0
	s_mov_b32 m0, s26
	v_lshl_add_u64 v[148:149], s[10:11], 0, v[132:133]
	ds_read_b128 v[214:217], v165 offset:32768
	ds_read_b128 v[218:221], v165 offset:33792
	ds_read_b128 v[222:225], v165 offset:34816
	ds_read_b128 v[226:229], v165 offset:35840
	ds_read_b128 v[230:233], v165 offset:36864
	ds_read_b128 v[234:237], v165 offset:37888
	ds_read_b128 v[238:241], v165 offset:38912
	ds_read_b128 v[242:245], v165 offset:39936
	global_load_lds_dwordx4 v[148:149], off
	v_lshl_add_u64 v[148:149], s[10:11], 0, v[130:131]
	s_mov_b32 m0, s27
	s_nop 0
	global_load_lds_dwordx4 v[148:149], off
	s_waitcnt vmcnt(8)
	s_waitcnt lgkmcnt(0)
	s_barrier
	s_setprio 1
	s_waitcnt lgkmcnt(0)
	v_mfma_f32_16x16x32_bf16 v[124:127], v[158:161], v[214:217], v[124:127]
	v_mfma_f32_16x16x32_bf16 v[120:123], v[170:173], v[214:217], v[120:123]
	v_mfma_f32_16x16x32_bf16 v[108:111], v[158:161], v[222:225], v[108:111]
	v_mfma_f32_16x16x32_bf16 v[104:107], v[170:173], v[222:225], v[104:107]
	v_mfma_f32_16x16x32_bf16 v[92:95], v[158:161], v[230:233], v[92:95]
	v_mfma_f32_16x16x32_bf16 v[88:91], v[170:173], v[230:233], v[88:91]
	v_mfma_f32_16x16x32_bf16 v[76:79], v[158:161], v[238:241], v[76:79]
	v_mfma_f32_16x16x32_bf16 v[72:75], v[170:173], v[238:241], v[72:75]
	v_mfma_f32_16x16x32_bf16 v[124:127], v[166:169], v[218:221], v[124:127]
	v_mfma_f32_16x16x32_bf16 v[120:123], v[174:177], v[218:221], v[120:123]
	v_mfma_f32_16x16x32_bf16 v[108:111], v[166:169], v[226:229], v[108:111]
	v_mfma_f32_16x16x32_bf16 v[104:107], v[174:177], v[226:229], v[104:107]
	v_mfma_f32_16x16x32_bf16 v[92:95], v[166:169], v[234:237], v[92:95]
	v_mfma_f32_16x16x32_bf16 v[88:91], v[174:177], v[234:237], v[88:91]
	v_mfma_f32_16x16x32_bf16 v[76:79], v[166:169], v[242:245], v[76:79]
	v_mfma_f32_16x16x32_bf16 v[72:75], v[174:177], v[242:245], v[72:75]
	s_setprio 0
	s_setprio 1
	v_mfma_f32_16x16x32_bf16 v[116:119], v[178:181], v[214:217], v[116:119]
	v_mfma_f32_16x16x32_bf16 v[112:115], v[206:209], v[214:217], v[112:115]
	v_mfma_f32_16x16x32_bf16 v[100:103], v[178:181], v[222:225], v[100:103]
	v_mfma_f32_16x16x32_bf16 v[96:99], v[206:209], v[222:225], v[96:99]
	v_mfma_f32_16x16x32_bf16 v[84:87], v[178:181], v[230:233], v[84:87]
	v_mfma_f32_16x16x32_bf16 v[80:83], v[206:209], v[230:233], v[80:83]
	v_mfma_f32_16x16x32_bf16 v[68:71], v[178:181], v[238:241], v[68:71]
	v_mfma_f32_16x16x32_bf16 v[64:67], v[206:209], v[238:241], v[64:67]
	v_mfma_f32_16x16x32_bf16 v[116:119], v[182:185], v[218:221], v[116:119]
	v_mfma_f32_16x16x32_bf16 v[112:115], v[210:213], v[218:221], v[112:115]
	v_mfma_f32_16x16x32_bf16 v[100:103], v[182:185], v[226:229], v[100:103]
	v_mfma_f32_16x16x32_bf16 v[96:99], v[210:213], v[226:229], v[96:99]
	v_mfma_f32_16x16x32_bf16 v[84:87], v[182:185], v[234:237], v[84:87]
	v_mfma_f32_16x16x32_bf16 v[80:83], v[210:213], v[234:237], v[80:83]
	v_mfma_f32_16x16x32_bf16 v[68:71], v[182:185], v[242:245], v[68:71]
	v_mfma_f32_16x16x32_bf16 v[64:67], v[210:213], v[242:245], v[64:67]
	s_setprio 0
	s_barrier
	s_add_i32 s10, s35, s14
	v_lshl_add_u64 v[138:139], v[138:139], 0, s[36:37]
	s_mov_b32 m0, s10
	ds_read_b128 v[214:217], v165 offset:49152
	ds_read_b128 v[218:221], v165 offset:50176
	ds_read_b128 v[222:225], v165 offset:51200
	ds_read_b128 v[226:229], v165 offset:52224
	ds_read_b128 v[230:233], v165 offset:53248
	ds_read_b128 v[234:237], v165 offset:54272
	ds_read_b128 v[238:241], v165 offset:55296
	ds_read_b128 v[242:245], v165 offset:56320
	global_load_lds_dwordx4 v[138:139], off
	s_add_i32 m0, s10, 0x2000
	s_add_u32 s8, s8, 0x40080
	v_lshl_add_u64 v[138:139], v[142:143], 0, s[36:37]
	s_addc_u32 s9, s9, 0
	s_add_i32 s10, s60, s14
	global_load_lds_dwordx4 v[138:139], off
	v_lshl_add_u64 v[138:139], s[8:9], 0, v[140:141]
	s_mov_b32 m0, s10
	s_nop 0
	global_load_lds_dwordx4 v[138:139], off
	v_lshl_add_u64 v[138:139], s[8:9], 0, v[128:129]
	s_add_i32 m0, s10, 0x2000
	s_nop 0
	global_load_lds_dwordx4 v[138:139], off
	v_lshl_add_u64 v[138:139], v[144:145], 0, s[36:37]
	s_mov_b32 m0, s28
	s_nop 0
	global_load_lds_dwordx4 v[138:139], off
	v_lshl_add_u64 v[138:139], v[146:147], 0, s[36:37]
	s_mov_b32 m0, s29
	s_nop 0
	global_load_lds_dwordx4 v[138:139], off
	s_waitcnt vmcnt(8)
	s_waitcnt lgkmcnt(0)
	s_barrier
	s_setprio 1
	s_waitcnt lgkmcnt(0)
	v_mfma_f32_16x16x32_bf16 v[60:63], v[158:161], v[214:217], v[60:63]
	v_mfma_f32_16x16x32_bf16 v[56:59], v[170:173], v[214:217], v[56:59]
	v_mfma_f32_16x16x32_bf16 v[44:47], v[158:161], v[222:225], v[44:47]
	v_mfma_f32_16x16x32_bf16 v[40:43], v[170:173], v[222:225], v[40:43]
	v_mfma_f32_16x16x32_bf16 v[28:31], v[158:161], v[230:233], v[28:31]
	v_mfma_f32_16x16x32_bf16 v[24:27], v[170:173], v[230:233], v[24:27]
	v_mfma_f32_16x16x32_bf16 v[12:15], v[158:161], v[238:241], v[12:15]
	v_mfma_f32_16x16x32_bf16 v[8:11], v[170:173], v[238:241], v[8:11]
	v_mfma_f32_16x16x32_bf16 v[60:63], v[166:169], v[218:221], v[60:63]
	v_mfma_f32_16x16x32_bf16 v[56:59], v[174:177], v[218:221], v[56:59]
	v_mfma_f32_16x16x32_bf16 v[44:47], v[166:169], v[226:229], v[44:47]
	v_mfma_f32_16x16x32_bf16 v[40:43], v[174:177], v[226:229], v[40:43]
	v_mfma_f32_16x16x32_bf16 v[28:31], v[166:169], v[234:237], v[28:31]
	v_mfma_f32_16x16x32_bf16 v[24:27], v[174:177], v[234:237], v[24:27]
	v_mfma_f32_16x16x32_bf16 v[12:15], v[166:169], v[242:245], v[12:15]
	v_mfma_f32_16x16x32_bf16 v[8:11], v[174:177], v[242:245], v[8:11]
	s_setprio 0
	s_setprio 1
	v_mfma_f32_16x16x32_bf16 v[52:55], v[178:181], v[214:217], v[52:55]
	v_mfma_f32_16x16x32_bf16 v[48:51], v[206:209], v[214:217], v[48:51]
	v_mfma_f32_16x16x32_bf16 v[36:39], v[178:181], v[222:225], v[36:39]
	v_mfma_f32_16x16x32_bf16 v[32:35], v[206:209], v[222:225], v[32:35]
	v_mfma_f32_16x16x32_bf16 v[20:23], v[178:181], v[230:233], v[20:23]
	v_mfma_f32_16x16x32_bf16 v[16:19], v[206:209], v[230:233], v[16:19]
	v_mfma_f32_16x16x32_bf16 v[4:7], v[178:181], v[238:241], v[4:7]
	v_mfma_f32_16x16x32_bf16 v[0:3], v[206:209], v[238:241], v[0:3]
	v_mfma_f32_16x16x32_bf16 v[52:55], v[182:185], v[218:221], v[52:55]
	v_mfma_f32_16x16x32_bf16 v[48:51], v[210:213], v[218:221], v[48:51]
	v_mfma_f32_16x16x32_bf16 v[36:39], v[182:185], v[226:229], v[36:39]
	v_mfma_f32_16x16x32_bf16 v[32:35], v[210:213], v[226:229], v[32:35]
	v_mfma_f32_16x16x32_bf16 v[20:23], v[182:185], v[234:237], v[20:23]
	v_mfma_f32_16x16x32_bf16 v[16:19], v[210:213], v[234:237], v[16:19]
	v_mfma_f32_16x16x32_bf16 v[4:7], v[182:185], v[242:245], v[4:7]
	v_mfma_f32_16x16x32_bf16 v[0:3], v[210:213], v[242:245], v[0:3]
	s_setprio 0
	s_add_i32 s59, s59, 2
	s_add_u32 s6, s6, 0x100
	s_addc_u32 s7, s7, 0
	s_add_u32 s57, s57, 0x100
	s_addc_u32 s58, s58, 0
	s_cmp_gt_u32 s59, 13
	s_cbranch_scc0 .LBB0_714
	s_and_b64 vcc, exec, s[46:47]
	s_cbranch_vccz .LBB0_717
	s_barrier
